# speedup vs baseline: 1.0223x; 1.0223x over previous
; __device__ __forceinline__ int opaque_tid() { int t = threadIdx.x; asm volatile("" : "+v"(t)); return t; }
; #define G_STA(bufoff, gbase, ld) G_STAGE(bufoff, gbase, RA0, RA1, ld)
; #define G_STB(bufoff, gbase, ld) G_STAGE(bufoff, gbase, RB0, RB1, ld)
; #define G_WAIT_V(n) asm volatile("s_waitcnt vmcnt(" #n ")" ::: "memory")
; #define G_BAR __builtin_amdgcn_s_barrier()
; template <bool PERM, class SchedT, class Epi>
; __device__ __forceinline__ void gemm_phase(LAS unsigned char* lds, const SchedT& S, const Epi& E) {
;     const int tid = opaque_tid(), wid = __builtin_amdgcn_readfirstlane(tid >> 6), lane = tid & 63, wr = wid >> 2, wc = wid & 3, fr = lane & 15, fq = lane >> 4;
;     int R0, C0, R1, C1; stage_rc(tid * 16, R0, C0); stage_rc(tid * 16 + 8192, R1, C1);
;     const unsigned RA0 = (unsigned)R0 * 2u, RA1 = (unsigned)R1 * 2u, RB0 = (unsigned)(PERM ? ((R0 & ~31) + perm32(R0 & 31)) : R0) * 2u, RB1 = (unsigned)(PERM ? ((R1 & ~31) + perm32(R1 & 31)) : R1) * 2u;
;     const unsigned CC0 = (unsigned)C0 * 2u, CC1 = (unsigned)C1 * 2u;
;     const size_t kstep = (size_t)(BK * 2);
;     const unsigned ldsw = (unsigned)wid * 1024u;
;     const int aoff = lds_byte(wr * 64 + fr, fq * 8), boff = lds_byte(wc * 32 + fr, fq * 8);
;     ...
;     UnitD cur, nxt; int ui = 0;
;     if (!S.get(0, cur)) return;
;     f32x4 acc[2][2][4][2];
; #pragma unroll
;     for (int a = 0; a < 2; ++a)
; #pragma unroll
;         for (int b = 0; b < 2; ++b)
; #pragma unroll
;             for (int m = 0; m < 4; ++m)
; #pragma unroll
;                 for (int n = 0; n < 2; ++n) acc[a][b][m][n] = (f32x4){0.f, 0.f, 0.f, 0.f};
;     bf16x8 At[4][2], B0[2][2], B1[2][2];
;     const char* cA = cur.A; const char* cB = cur.B;
;     int lda = cur.lda, K = cur.K;
;     ...
;     G_STB(G_SB(0, 0), cB, K); G_STA(G_SA(0, 0), cA, lda); G_STB(G_SB(0, 1), cB + HSTEP(K), K); G_STA(G_SA(0, 1), cA + HSTEP(lda), lda);
;     if (wr == 1) G_BAR;
;     G_WAIT_V(4); G_BAR;
;     G_STB(G_SB(1, 0), cB + kstep, K); G_STA(G_SA(1, 0), cA + kstep, lda); G_STB(G_SB(1, 1), cB + HSTEP(K) + kstep, K);
;     G_WAIT_V(6); G_BAR;
.LBB0_147:
	v_lshrrev_b32_e32 v16, 1, v6
	v_and_b32_e32 v16, 24, v16
	v_and_b32_e32 v250, 63, v6
	v_lshrrev_b32_e32 v253, 6, v6
	v_lshlrev_b32_e32 v253, 10, v253
	v_add_u32_e32 v253, 0x22000, v253
	v_and_b32_e32 v254, 15, v250
	v_lshrrev_b32_e32 v255, 4, v250
	v_bfe_u32 v251, v254, 1, 2
	v_xor_b32_e32 v251, v251, v255
	v_lshlrev_b32_e32 v251, 4, v251
	v_lshl_add_u32 v251, v254, 6, v251
	v_add_u32_e32 v251, v251, v253
	v_lshrrev_b32_e32 v254, 2, v250
	v_and_b32_e32 v255, 3, v250
	v_bfe_u32 v252, v254, 1, 2
	v_xor_b32_e32 v252, v252, v255
	v_lshlrev_b32_e32 v252, 4, v252
	v_lshl_add_u32 v252, v254, 6, v252
	v_add_u32_e32 v252, v252, v253
	v_lshlrev_b32_e32 v255, 3, v255
	v_lshl_add_u64 v[12:13], s[26:27], 0, v[0:1]
	v_mov_b32_e32 v135, v1
	v_and_b32_e32 v11, 15, v6
	v_lshlrev_b32_e32 v17, 1, v16
	v_lshlrev_b32_e32 v6, 2, v6
	s_lshl_b32 s7, s7, 5
	v_lshl_add_u64 v[14:15], s[26:27], 0, v[134:135]
	v_mov_b32_e32 v3, v1
	v_lshl_or_b32 v137, s16, 6, v254
	v_lshl_or_b32 v11, v11, 6, v17
	s_lshl_b32 s10, s16, 13
	v_and_b32_e32 v6, 32, v6
	s_and_b32 s7, s7, 0x60
	v_lshl_add_u64 v[12:13], v[12:13], 0, s[78:79]
	s_add_i32 m0, s35, 0x18000
	v_lshl_add_u64 v[2:3], s[12:13], 0, v[2:3]
	v_mov_b32_e32 v5, v1
	v_bitop3_b32 v17, v11, s10, v6 bitop3:0xde
	s_lshl_b32 s10, s7, 7
	s_waitcnt vmcnt(4)
	s_barrier
	global_load_lds_dwordx4 v[12:13], off
	v_lshl_add_u64 v[12:13], v[14:15], 0, s[78:79]
	s_add_i32 m0, s35, 0x1a000
	s_add_i32 s39, s35, 0x8000
	s_add_i32 s40, s35, 0xa000
	v_lshl_add_u64 v[4:5], s[12:13], 0, v[4:5]
	v_bitop3_b32 v139, v11, s10, v6 bitop3:0xde
	global_load_lds_dwordx4 v[12:13], off
	v_lshl_add_u64 v[2:3], v[2:3], 0, s[78:79]
	s_mov_b32 m0, s39
	s_add_u32 s10, s26, 0x20080
	global_load_lds_dwordx4 v[2:3], off
	v_lshl_add_u64 v[2:3], v[4:5], 0, s[78:79]
	s_mov_b32 m0, s40
	s_addc_u32 s11, s27, 0
	global_load_lds_dwordx4 v[2:3], off
	v_lshl_add_u64 v[2:3], s[10:11], 0, v[0:1]
	s_add_i32 m0, s35, 0x1c000
	v_or_b32_e32 v144, s7, v255
	global_load_lds_dwordx4 v[2:3], off
	v_lshl_add_u64 v[2:3], s[10:11], 0, v[134:135]
	s_add_i32 m0, s35, 0x1e000
	s_mov_b32 s41, 0
	global_load_lds_dwordx4 v[2:3], off
	s_waitcnt vmcnt(6)
	v_and_b32_e32 v2, 1, v7
	v_lshlrev_b32_e32 v3, 1, v8
	v_lshl_add_u32 v136, v2, 6, v3
	v_and_b32_e32 v2, 1, v9
	v_lshlrev_b32_e32 v3, 1, v10
	v_lshl_add_u32 v138, v2, 6, v3
	v_add_u32_e32 v145, 0, v17
	s_barrier

; #define G_STA(bufoff, gbase, ld) G_STAGE(bufoff, gbase, RA0, RA1, ld)
; #define G_STB(bufoff, gbase, ld) G_STAGE(bufoff, gbase, RB0, RB1, ld)
; #define G_LDA(dst, b, h) do { _Pragma("unroll") for (int m = 0; m < 4; ++m) _Pragma("unroll") for (int k = 0; k < 2; ++k) dst[m][k] = *(const LAS bf16x8*)(lds + G_SA(b, h) + aoff + m * 2048 + k * 1024); } while (0)
; #define G_LDB(dst, b, h) do { _Pragma("unroll") for (int n = 0; n < 2; ++n) _Pragma("unroll") for (int k = 0; k < 2; ++k) dst[n][k] = *(const LAS bf16x8*)(lds + G_SB(b, h) + boff + n * 2048 + k * 1024); } while (0)
; #define G_MMA(ai, bj, At, Bt) do { __builtin_amdgcn_s_setprio(1); _Pragma("unroll") for (int m = 0; m < 4; ++m) _Pragma("unroll") for (int n = 0; n < 2; ++n) _Pragma("unroll") for (int k = 0; k < 2; ++k) \
;         acc[ai][bj][m][n] = __builtin_amdgcn_mfma_f32_16x16x32_bf16(Bt[n][k], At[m][k], acc[ai][bj][m][n], 0, 0, 0); __builtin_amdgcn_s_setprio(0); } while (0)
; #define G_WAIT_L(n) asm volatile("s_waitcnt lgkmcnt(" #n ")" ::: "memory")
; #define G_BAR __builtin_amdgcn_s_barrier()
; #define G_SCHED __builtin_amdgcn_sched_barrier(0)
; template <bool PERM, class SchedT, class Epi>
; __device__ __forceinline__ void gemm_phase(LAS unsigned char* lds, const SchedT& S, const Epi& E) {
;     ...
;         for (int t = 0; t < nt; t += 2) {
;             const bool last = (t == nt - 2);
;             const char* a1 = cA + (size_t)(t + 1) * kstep;
;             const char* a2 = last ? nA : cA + (size_t)(t + 2) * kstep; const char* b2 = last ? nB : cB + (size_t)(t + 2) * kstep;
;             const char* a3 = a2 + kstep; const char* b3 = b2 + kstep;
;             const int wlda = last ? nlda : lda, wK = last ? nK : K;
;             G_LDB(B0, 0, 0); G_SCHED; G_LDA(At, 0, 0); G_STA(G_SA(1, 1), a1 + HSTEP(lda), lda);
;             G_WAIT_L(8); G_BAR; G_WAIT_L(0); G_MMA(0, 0, At, B0); G_BAR; G_SCHED;
;             G_LDB(B1, 0, 1); G_STB(G_SB(0, 0), b2, wK);
;             G_BAR; G_WAIT_L(0); G_MMA(0, 1, At, B1); G_BAR;
;             G_LDA(At, 0, 1); G_STA(G_SA(0, 0), a2, wlda);
;             G_BAR; G_WAIT_L(0); G_MMA(1, 0, At, B0); G_BAR; G_SCHED;
.LBB0_165:
	s_add_u32 s26, s12, s22
	s_addc_u32 s27, s13, s23
	s_add_u32 s28, s26, 0x100
	s_addc_u32 s29, s27, 0
	s_add_u32 s51, s7, s22
	s_addc_u32 s52, s49, s23
	s_cmpk_eq_i32 s22, 0x300
	s_cselect_b64 s[30:31], -1, 0
	s_and_b64 s[26:27], s[30:31], exec
	s_cselect_b32 s29, s45, s29
	s_cselect_b32 s28, s46, s28
	s_cselect_b32 s27, s47, s52
	s_cselect_b32 s26, s48, s51
	s_and_b64 s[30:31], s[24:25], s[30:31]
	s_and_b64 s[30:31], s[30:31], exec
	s_cselect_b32 s30, s44, s6
	s_add_i32 s31, 0, 0x10000
	v_add_u32_e32 v160, s31, v139
	ds_read_b128 v[146:149], v160
	ds_read_b128 v[150:153], v160 offset:1024
	ds_read_b128 v[154:157], v160 offset:2048
	ds_read_b128 v[160:163], v160 offset:3072
	v_lshl_add_u64 v[208:209], v[140:141], 0, s[22:23]
	s_add_i32 m0, s35, 0xc000
	ds_read_b128 v[164:167], v145
	ds_read_b128 v[168:171], v145 offset:1024
	ds_read_b128 v[172:175], v145 offset:2048
	ds_read_b128 v[176:179], v145 offset:3072
	ds_read_b128 v[192:195], v145 offset:4096
	ds_read_b128 v[196:199], v145 offset:5120
	ds_read_b128 v[200:203], v145 offset:6144
	ds_read_b128 v[204:207], v145 offset:7168
	global_load_lds_dwordx4 v[208:209], off
	v_lshl_add_u64 v[208:209], v[142:143], 0, s[22:23]
	s_add_i32 m0, s35, 0xe000
	s_nop 0
	global_load_lds_dwordx4 v[208:209], off
	s_waitcnt lgkmcnt(8)
	s_barrier
	s_waitcnt lgkmcnt(0)
	s_setprio 1
	s_waitcnt lgkmcnt(0)
	v_mfma_f32_16x16x32_bf16 v[126:129], v[146:149], v[164:167], v[126:129]
	v_mfma_f32_16x16x32_bf16 v[122:125], v[154:157], v[164:167], v[122:125]
	v_mfma_f32_16x16x32_bf16 v[118:121], v[146:149], v[172:175], v[118:121]
	v_mfma_f32_16x16x32_bf16 v[110:113], v[154:157], v[172:175], v[110:113]
	v_mfma_f32_16x16x32_bf16 v[102:105], v[146:149], v[192:195], v[102:105]
	v_mfma_f32_16x16x32_bf16 v[94:97], v[154:157], v[192:195], v[94:97]
	v_mfma_f32_16x16x32_bf16 v[86:89], v[146:149], v[200:203], v[86:89]
	v_mfma_f32_16x16x32_bf16 v[78:81], v[154:157], v[200:203], v[78:81]
	v_mfma_f32_16x16x32_bf16 v[126:129], v[150:153], v[168:171], v[126:129]
	v_mfma_f32_16x16x32_bf16 v[122:125], v[160:163], v[168:171], v[122:125]
	v_mfma_f32_16x16x32_bf16 v[118:121], v[150:153], v[176:179], v[118:121]
	v_mfma_f32_16x16x32_bf16 v[110:113], v[160:163], v[176:179], v[110:113]
	v_mfma_f32_16x16x32_bf16 v[102:105], v[150:153], v[196:199], v[102:105]
	v_mfma_f32_16x16x32_bf16 v[94:97], v[160:163], v[196:199], v[94:97]
	v_mfma_f32_16x16x32_bf16 v[86:89], v[150:153], v[204:207], v[86:89]
	v_mfma_f32_16x16x32_bf16 v[78:81], v[160:163], v[204:207], v[78:81]
	s_setprio 0
	s_barrier
	s_add_i32 s51, 0, 0x14000
	s_add_i32 s31, s31, s34
	v_add_u32_e32 v220, s51, v139
	v_lshl_add_u64 v[224:225], s[26:27], 0, v[0:1]
	s_mov_b32 m0, s31
	ds_read_b128 v[208:211], v220
	ds_read_b128 v[212:215], v220 offset:1024
	ds_read_b128 v[216:219], v220 offset:2048
	ds_read_b128 v[220:223], v220 offset:3072
	global_load_lds_dwordx4 v[224:225], off
	v_lshl_add_u64 v[230:231], s[26:27], 0, v[134:135]
	s_add_i32 m0, s31, 0x2000
	s_nop 0
	global_load_lds_dwordx4 v[230:231], off
	s_barrier
	s_waitcnt lgkmcnt(0)
	s_setprio 1
	s_waitcnt lgkmcnt(0)
	v_mfma_f32_16x16x32_bf16 v[114:117], v[208:211], v[164:167], v[114:117]
	v_mfma_f32_16x16x32_bf16 v[106:109], v[216:219], v[164:167], v[106:109]
	v_mfma_f32_16x16x32_bf16 v[98:101], v[208:211], v[172:175], v[98:101]
	v_mfma_f32_16x16x32_bf16 v[90:93], v[216:219], v[172:175], v[90:93]
	v_mfma_f32_16x16x32_bf16 v[82:85], v[208:211], v[192:195], v[82:85]
	v_mfma_f32_16x16x32_bf16 v[74:77], v[216:219], v[192:195], v[74:77]
	v_mfma_f32_16x16x32_bf16 v[70:73], v[208:211], v[200:203], v[70:73]
	v_mfma_f32_16x16x32_bf16 v[66:69], v[216:219], v[200:203], v[66:69]
	v_mfma_f32_16x16x32_bf16 v[114:117], v[212:215], v[168:171], v[114:117]
	v_mfma_f32_16x16x32_bf16 v[106:109], v[220:223], v[168:171], v[106:109]
	v_mfma_f32_16x16x32_bf16 v[98:101], v[212:215], v[176:179], v[98:101]
	v_mfma_f32_16x16x32_bf16 v[90:93], v[220:223], v[176:179], v[90:93]
	v_mfma_f32_16x16x32_bf16 v[82:85], v[212:215], v[196:199], v[82:85]
	v_mfma_f32_16x16x32_bf16 v[74:77], v[220:223], v[196:199], v[74:77]
	v_mfma_f32_16x16x32_bf16 v[70:73], v[212:215], v[204:207], v[70:73]
	v_mfma_f32_16x16x32_bf16 v[66:69], v[220:223], v[204:207], v[66:69]
	s_setprio 0
	s_mov_b32 m0, s35
	v_mad_u64_u32 v[232:233], s[52:53], s30, v131, v[130:131]
	s_barrier
	ds_read_b128 v[164:167], v145 offset:16384
	ds_read_b128 v[168:171], v145 offset:17408
	ds_read_b128 v[172:175], v145 offset:18432
	ds_read_b128 v[176:179], v145 offset:19456
	ds_read_b128 v[192:195], v145 offset:20480
	ds_read_b128 v[196:199], v145 offset:21504
	ds_read_b128 v[200:203], v145 offset:22528
	ds_read_b128 v[204:207], v145 offset:23552
	global_load_lds_dwordx4 v232, s[28:29]
	v_mad_u64_u32 v[234:235], s[52:53], s30, v133, v[132:133]
	s_mov_b32 m0, s36
	v_mov_b32_e32 v233, v1
	global_load_lds_dwordx4 v234, s[28:29]
	s_barrier
	s_waitcnt lgkmcnt(0)
	v_mov_b32_e32 v235, v1
	v_lshl_add_u64 v[236:237], s[28:29], 0, v[232:233]
	v_lshl_add_u64 v[238:239], s[28:29], 0, v[234:235]
	s_setprio 1
	s_waitcnt lgkmcnt(0)
	v_mfma_f32_16x16x32_bf16 v[62:65], v[146:149], v[164:167], v[62:65]
	v_mfma_f32_16x16x32_bf16 v[58:61], v[154:157], v[164:167], v[58:61]
	v_mfma_f32_16x16x32_bf16 v[54:57], v[146:149], v[172:175], v[54:57]
	v_mfma_f32_16x16x32_bf16 v[46:49], v[154:157], v[172:175], v[46:49]
	v_mfma_f32_16x16x32_bf16 v[38:41], v[146:149], v[192:195], v[38:41]
	v_mfma_f32_16x16x32_bf16 v[30:33], v[154:157], v[192:195], v[30:33]
	v_mfma_f32_16x16x32_bf16 v[22:25], v[146:149], v[200:203], v[22:25]
	v_mfma_f32_16x16x32_bf16 v[14:17], v[154:157], v[200:203], v[14:17]
	v_mfma_f32_16x16x32_bf16 v[62:65], v[150:153], v[168:171], v[62:65]
	v_mfma_f32_16x16x32_bf16 v[58:61], v[160:163], v[168:171], v[58:61]
	v_mfma_f32_16x16x32_bf16 v[54:57], v[150:153], v[176:179], v[54:57]
	v_mfma_f32_16x16x32_bf16 v[46:49], v[160:163], v[176:179], v[46:49]
	v_mfma_f32_16x16x32_bf16 v[38:41], v[150:153], v[196:199], v[38:41]
	v_mfma_f32_16x16x32_bf16 v[30:33], v[160:163], v[196:199], v[30:33]
	v_mfma_f32_16x16x32_bf16 v[22:25], v[150:153], v[204:207], v[22:25]
	v_mfma_f32_16x16x32_bf16 v[14:17], v[160:163], v[204:207], v[14:17]
	s_setprio 0
	s_barrier
; #define G_STA(bufoff, gbase, ld) G_STAGE(bufoff, gbase, RA0, RA1, ld)
; #define G_STB(bufoff, gbase, ld) G_STAGE(bufoff, gbase, RB0, RB1, ld)
; #define G_LDA(dst, b, h) do { _Pragma("unroll") for (int m = 0; m < 4; ++m) _Pragma("unroll") for (int k = 0; k < 2; ++k) dst[m][k] = *(const LAS bf16x8*)(lds + G_SA(b, h) + aoff + m * 2048 + k * 1024); } while (0)
; #define G_LDB(dst, b, h) do { _Pragma("unroll") for (int n = 0; n < 2; ++n) _Pragma("unroll") for (int k = 0; k < 2; ++k) dst[n][k] = *(const LAS bf16x8*)(lds + G_SB(b, h) + boff + n * 2048 + k * 1024); } while (0)
; #define G_MMA(ai, bj, At, Bt) do { __builtin_amdgcn_s_setprio(1); _Pragma("unroll") for (int m = 0; m < 4; ++m) _Pragma("unroll") for (int n = 0; n < 2; ++n) _Pragma("unroll") for (int k = 0; k < 2; ++k) \
;         acc[ai][bj][m][n] = __builtin_amdgcn_mfma_f32_16x16x32_bf16(Bt[n][k], At[m][k], acc[ai][bj][m][n], 0, 0, 0); __builtin_amdgcn_s_setprio(0); } while (0)
; #define G_WAIT_V(n) asm volatile("s_waitcnt vmcnt(" #n ")" ::: "memory")
; #define G_WAIT_L(n) asm volatile("s_waitcnt lgkmcnt(" #n ")" ::: "memory")
; #define G_BAR __builtin_amdgcn_s_barrier()
; #define G_SCHED __builtin_amdgcn_sched_barrier(0)
; template <bool PERM, class SchedT, class Epi>
; __device__ __forceinline__ void gemm_phase(LAS unsigned char* lds, const SchedT& S, const Epi& E) {
;     ...
;             G_STB(G_SB(0, 1), b2 + HSTEP(wK), wK);
;             G_WAIT_V(6); G_BAR; G_MMA(1, 1, At, B1); G_BAR;
;             G_LDB(B0, 1, 0); G_SCHED; G_LDA(At, 1, 0); G_STA(G_SA(0, 1), a2 + HSTEP(wlda), wlda);
;             G_WAIT_L(8); G_BAR; G_WAIT_L(0); G_MMA(0, 0, At, B0); G_BAR; G_SCHED;
;             G_LDB(B1, 1, 1); G_STB(G_SB(1, 0), b3, wK);
;             G_BAR; G_WAIT_L(0); G_MMA(0, 1, At, B1); G_BAR;
;             G_LDA(At, 1, 1); G_STA(G_SA(1, 0), a3, wlda);
;             G_BAR; G_WAIT_L(0); G_MMA(1, 0, At, B0); G_BAR; G_SCHED;
	s_add_u32 s52, s26, 0x20000
	s_addc_u32 s53, s27, 0
	s_add_i32 s31, s51, s34
	v_lshl_add_u64 v[146:147], s[52:53], 0, v[0:1]
	s_mov_b32 m0, s31
	s_nop 0
	global_load_lds_dwordx4 v[146:147], off
	v_lshl_add_u64 v[146:147], s[52:53], 0, v[134:135]
	s_add_i32 m0, s31, 0x2000
	s_nop 0
	global_load_lds_dwordx4 v[146:147], off
	s_waitcnt vmcnt(6)
	s_barrier
	s_setprio 1
	v_mfma_f32_16x16x32_bf16 v[50:53], v[208:211], v[164:167], v[50:53]
	v_mfma_f32_16x16x32_bf16 v[42:45], v[216:219], v[164:167], v[42:45]
	v_mfma_f32_16x16x32_bf16 v[34:37], v[208:211], v[172:175], v[34:37]
	v_mfma_f32_16x16x32_bf16 v[26:29], v[216:219], v[172:175], v[26:29]
	v_mfma_f32_16x16x32_bf16 v[18:21], v[208:211], v[192:195], v[18:21]
	v_mfma_f32_16x16x32_bf16 v[10:13], v[216:219], v[192:195], v[10:13]
	v_mfma_f32_16x16x32_bf16 v[6:9], v[208:211], v[200:203], v[6:9]
	v_mfma_f32_16x16x32_bf16 v[2:5], v[216:219], v[200:203], v[2:5]
	v_mfma_f32_16x16x32_bf16 v[50:53], v[212:215], v[168:171], v[50:53]
	v_mfma_f32_16x16x32_bf16 v[42:45], v[220:223], v[168:171], v[42:45]
	v_mfma_f32_16x16x32_bf16 v[34:37], v[212:215], v[176:179], v[34:37]
	v_mfma_f32_16x16x32_bf16 v[26:29], v[220:223], v[176:179], v[26:29]
	v_mfma_f32_16x16x32_bf16 v[18:21], v[212:215], v[196:199], v[18:21]
	v_mfma_f32_16x16x32_bf16 v[10:13], v[220:223], v[196:199], v[10:13]
	v_mfma_f32_16x16x32_bf16 v[6:9], v[212:215], v[204:207], v[6:9]
	v_mfma_f32_16x16x32_bf16 v[2:5], v[220:223], v[204:207], v[2:5]
	s_setprio 0
	s_add_i32 s51, 0, 0x18000
	v_add_u32_e32 v160, s51, v139
	s_barrier
	ds_read_b128 v[146:149], v160
	ds_read_b128 v[150:153], v160 offset:1024
	ds_read_b128 v[154:157], v160 offset:2048
	ds_read_b128 v[160:163], v160 offset:3072
	s_ashr_i32 s31, s30, 31
	s_lshl_b64 s[30:31], s[30:31], 8
	s_add_u32 s28, s28, s30
	s_addc_u32 s29, s29, s31
	s_mov_b32 m0, s37
	ds_read_b128 v[164:167], v145 offset:32768
	ds_read_b128 v[168:171], v145 offset:33792
	ds_read_b128 v[172:175], v145 offset:34816
	ds_read_b128 v[176:179], v145 offset:35840
	ds_read_b128 v[192:195], v145 offset:36864
	ds_read_b128 v[196:199], v145 offset:37888
	ds_read_b128 v[200:203], v145 offset:38912
	ds_read_b128 v[204:207], v145 offset:39936
	global_load_lds_dwordx4 v232, s[28:29]
	s_mov_b32 m0, s38
	s_nop 0
	global_load_lds_dwordx4 v234, s[28:29]
	s_waitcnt lgkmcnt(8)
	s_barrier
	s_waitcnt lgkmcnt(0)
	s_setprio 1
	s_waitcnt lgkmcnt(0)
	v_mfma_f32_16x16x32_bf16 v[126:129], v[146:149], v[164:167], v[126:129]
	v_mfma_f32_16x16x32_bf16 v[122:125], v[154:157], v[164:167], v[122:125]
	v_mfma_f32_16x16x32_bf16 v[118:121], v[146:149], v[172:175], v[118:121]
	v_mfma_f32_16x16x32_bf16 v[110:113], v[154:157], v[172:175], v[110:113]
	v_mfma_f32_16x16x32_bf16 v[102:105], v[146:149], v[192:195], v[102:105]
	v_mfma_f32_16x16x32_bf16 v[94:97], v[154:157], v[192:195], v[94:97]
	v_mfma_f32_16x16x32_bf16 v[86:89], v[146:149], v[200:203], v[86:89]
	v_mfma_f32_16x16x32_bf16 v[78:81], v[154:157], v[200:203], v[78:81]
	v_mfma_f32_16x16x32_bf16 v[126:129], v[150:153], v[168:171], v[126:129]
	v_mfma_f32_16x16x32_bf16 v[122:125], v[160:163], v[168:171], v[122:125]
	v_mfma_f32_16x16x32_bf16 v[118:121], v[150:153], v[176:179], v[118:121]
	v_mfma_f32_16x16x32_bf16 v[110:113], v[160:163], v[176:179], v[110:113]
	v_mfma_f32_16x16x32_bf16 v[102:105], v[150:153], v[196:199], v[102:105]
	v_mfma_f32_16x16x32_bf16 v[94:97], v[160:163], v[196:199], v[94:97]
	v_mfma_f32_16x16x32_bf16 v[86:89], v[150:153], v[204:207], v[86:89]
	v_mfma_f32_16x16x32_bf16 v[78:81], v[160:163], v[204:207], v[78:81]
	s_setprio 0
	s_barrier
	s_add_i32 s28, 0, 0x1c000
	s_add_i32 s29, s51, s34
	v_add_u32_e32 v220, s28, v139
	v_lshl_add_u64 v[224:225], v[224:225], 0, s[78:79]
	s_mov_b32 m0, s29
	ds_read_b128 v[208:211], v220
	ds_read_b128 v[212:215], v220 offset:1024
	ds_read_b128 v[216:219], v220 offset:2048
	ds_read_b128 v[220:223], v220 offset:3072
	global_load_lds_dwordx4 v[224:225], off
	v_lshl_add_u64 v[224:225], v[230:231], 0, s[78:79]
	s_add_i32 m0, s29, 0x2000
	s_nop 0
	global_load_lds_dwordx4 v[224:225], off
	s_barrier
	s_waitcnt lgkmcnt(0)
	s_setprio 1
	s_waitcnt lgkmcnt(0)
	v_mfma_f32_16x16x32_bf16 v[114:117], v[208:211], v[164:167], v[114:117]
	v_mfma_f32_16x16x32_bf16 v[106:109], v[216:219], v[164:167], v[106:109]
	v_mfma_f32_16x16x32_bf16 v[98:101], v[208:211], v[172:175], v[98:101]
	v_mfma_f32_16x16x32_bf16 v[90:93], v[216:219], v[172:175], v[90:93]
	v_mfma_f32_16x16x32_bf16 v[82:85], v[208:211], v[192:195], v[82:85]
	v_mfma_f32_16x16x32_bf16 v[74:77], v[216:219], v[192:195], v[74:77]
	v_mfma_f32_16x16x32_bf16 v[70:73], v[208:211], v[200:203], v[70:73]
	v_mfma_f32_16x16x32_bf16 v[66:69], v[216:219], v[200:203], v[66:69]
	v_mfma_f32_16x16x32_bf16 v[114:117], v[212:215], v[168:171], v[114:117]
	v_mfma_f32_16x16x32_bf16 v[106:109], v[220:223], v[168:171], v[106:109]
	v_mfma_f32_16x16x32_bf16 v[98:101], v[212:215], v[176:179], v[98:101]
	v_mfma_f32_16x16x32_bf16 v[90:93], v[220:223], v[176:179], v[90:93]
	v_mfma_f32_16x16x32_bf16 v[82:85], v[212:215], v[196:199], v[82:85]
	v_mfma_f32_16x16x32_bf16 v[74:77], v[220:223], v[196:199], v[74:77]
	v_mfma_f32_16x16x32_bf16 v[70:73], v[212:215], v[204:207], v[70:73]
	v_mfma_f32_16x16x32_bf16 v[66:69], v[220:223], v[204:207], v[66:69]
	s_setprio 0
	s_mov_b32 m0, s39
	v_lshl_add_u64 v[224:225], v[236:237], 0, s[78:79]
	s_barrier
	ds_read_b128 v[164:167], v145 offset:49152
	ds_read_b128 v[168:171], v145 offset:50176
	ds_read_b128 v[172:175], v145 offset:51200
	ds_read_b128 v[176:179], v145 offset:52224
	ds_read_b128 v[192:195], v145 offset:53248
	ds_read_b128 v[196:199], v145 offset:54272
	ds_read_b128 v[200:203], v145 offset:55296
	ds_read_b128 v[204:207], v145 offset:56320
	global_load_lds_dwordx4 v[224:225], off
	v_lshl_add_u64 v[224:225], v[238:239], 0, s[78:79]
	s_mov_b32 m0, s40
	s_nop 0
	global_load_lds_dwordx4 v[224:225], off
	s_barrier
; #define G_STB(bufoff, gbase, ld) G_STAGE(bufoff, gbase, RB0, RB1, ld)
; #define G_MMA(ai, bj, At, Bt) do { __builtin_amdgcn_s_setprio(1); _Pragma("unroll") for (int m = 0; m < 4; ++m) _Pragma("unroll") for (int n = 0; n < 2; ++n) _Pragma("unroll") for (int k = 0; k < 2; ++k) \
;         acc[ai][bj][m][n] = __builtin_amdgcn_mfma_f32_16x16x32_bf16(Bt[n][k], At[m][k], acc[ai][bj][m][n], 0, 0, 0); __builtin_amdgcn_s_setprio(0); } while (0)
; #define G_WAIT_V(n) asm volatile("s_waitcnt vmcnt(" #n ")" ::: "memory")
; #define G_WAIT_L(n) asm volatile("s_waitcnt lgkmcnt(" #n ")" ::: "memory")
; #define G_BAR __builtin_amdgcn_s_barrier()
; #define G_SCHED __builtin_amdgcn_sched_barrier(0)
; template <bool PERM, class SchedT, class Epi>
; __device__ __forceinline__ void gemm_phase(LAS unsigned char* lds, const SchedT& S, const Epi& E) {
;     ...
;             G_BAR; G_WAIT_L(0); G_MMA(1, 0, At, B0); G_BAR; G_SCHED;
;             G_STB(G_SB(1, 1), b3 + HSTEP(wK), wK);
;             G_WAIT_V(6); G_BAR; G_MMA(1, 1, At, B1); G_BAR;
;         }
	s_waitcnt lgkmcnt(0)
	s_setprio 1
	s_waitcnt lgkmcnt(0)
	v_mfma_f32_16x16x32_bf16 v[62:65], v[146:149], v[164:167], v[62:65]
	v_mfma_f32_16x16x32_bf16 v[58:61], v[154:157], v[164:167], v[58:61]
	v_mfma_f32_16x16x32_bf16 v[54:57], v[146:149], v[172:175], v[54:57]
	v_mfma_f32_16x16x32_bf16 v[46:49], v[154:157], v[172:175], v[46:49]
	v_mfma_f32_16x16x32_bf16 v[38:41], v[146:149], v[192:195], v[38:41]
	v_mfma_f32_16x16x32_bf16 v[30:33], v[154:157], v[192:195], v[30:33]
	v_mfma_f32_16x16x32_bf16 v[22:25], v[146:149], v[200:203], v[22:25]
	v_mfma_f32_16x16x32_bf16 v[14:17], v[154:157], v[200:203], v[14:17]
	v_mfma_f32_16x16x32_bf16 v[62:65], v[150:153], v[168:171], v[62:65]
	v_mfma_f32_16x16x32_bf16 v[58:61], v[160:163], v[168:171], v[58:61]
	v_mfma_f32_16x16x32_bf16 v[54:57], v[150:153], v[176:179], v[54:57]
	v_mfma_f32_16x16x32_bf16 v[46:49], v[160:163], v[176:179], v[46:49]
	v_mfma_f32_16x16x32_bf16 v[38:41], v[150:153], v[196:199], v[38:41]
	v_mfma_f32_16x16x32_bf16 v[30:33], v[160:163], v[196:199], v[30:33]
	v_mfma_f32_16x16x32_bf16 v[22:25], v[150:153], v[204:207], v[22:25]
	v_mfma_f32_16x16x32_bf16 v[14:17], v[160:163], v[204:207], v[14:17]
	s_setprio 0
	s_barrier
	s_add_u32 s26, s26, 0x20080
	s_addc_u32 s27, s27, 0
	s_add_i32 s28, s28, s34
	v_lshl_add_u64 v[146:147], s[26:27], 0, v[0:1]
	s_mov_b32 m0, s28
	s_nop 0
	global_load_lds_dwordx4 v[146:147], off
	v_lshl_add_u64 v[146:147], s[26:27], 0, v[134:135]
	s_add_i32 m0, s28, 0x2000
	s_nop 0
	global_load_lds_dwordx4 v[146:147], off
	s_waitcnt vmcnt(6)
	s_barrier
	s_setprio 1
	v_mfma_f32_16x16x32_bf16 v[50:53], v[208:211], v[164:167], v[50:53]
	v_mfma_f32_16x16x32_bf16 v[42:45], v[216:219], v[164:167], v[42:45]
	v_mfma_f32_16x16x32_bf16 v[34:37], v[208:211], v[172:175], v[34:37]
	v_mfma_f32_16x16x32_bf16 v[26:29], v[216:219], v[172:175], v[26:29]
	v_mfma_f32_16x16x32_bf16 v[18:21], v[208:211], v[192:195], v[18:21]
	v_mfma_f32_16x16x32_bf16 v[10:13], v[216:219], v[192:195], v[10:13]
	v_mfma_f32_16x16x32_bf16 v[6:9], v[208:211], v[200:203], v[6:9]
	v_mfma_f32_16x16x32_bf16 v[2:5], v[216:219], v[200:203], v[2:5]
	v_mfma_f32_16x16x32_bf16 v[50:53], v[212:215], v[168:171], v[50:53]
	v_mfma_f32_16x16x32_bf16 v[42:45], v[220:223], v[168:171], v[42:45]
	v_mfma_f32_16x16x32_bf16 v[34:37], v[212:215], v[176:179], v[34:37]
	v_mfma_f32_16x16x32_bf16 v[26:29], v[220:223], v[176:179], v[26:29]
	v_mfma_f32_16x16x32_bf16 v[18:21], v[212:215], v[196:199], v[18:21]
	v_mfma_f32_16x16x32_bf16 v[10:13], v[220:223], v[196:199], v[10:13]
	v_mfma_f32_16x16x32_bf16 v[6:9], v[212:215], v[204:207], v[6:9]
	v_mfma_f32_16x16x32_bf16 v[2:5], v[220:223], v[204:207], v[2:5]
	s_setprio 0
	s_add_i32 s50, s50, 2
	s_add_u32 s22, s22, 0x100
	s_addc_u32 s23, s23, 0
	s_cmp_gt_u32 s50, 5
	s_barrier
	s_cbranch_scc0 .LBB0_165
; __device__ __forceinline__ unsigned cvt_pk(float lo, float hi) { unsigned r; asm volatile("v_cvt_pk_bf16_f32 %0, %1, %2" : "=v"(r) : "v"(lo), "v"(hi)); return r; }
; #define GAS __attribute__((address_space(1)))
;     __device__ __forceinline__ void operator()(const f32x4 (&acc)[2][2][4][2], const UnitD& u, int wr, int wc, int fr, int fq) const {
;         const int row0 = u.pm * BM + wr * 64 + fr, col0 = u.pn * BM + wc * 32 + 8 * fq;
;         GAS bf16_t* C = (GAS bf16_t*)(unsigned long long)u.C;
; #pragma unroll
;         for (int ai = 0; ai < 2; ++ai)
; #pragma unroll
;             for (int m = 0; m < 4; ++m) { GAS bf16_t* rowp = C + (size_t)(row0 + ai * HALF + m * 16) * u.ldc + col0;
; #pragma unroll
;                 for (int bj = 0; bj < 2; ++bj) { const f32x4 v0 = acc[ai][bj][m][0], v1 = acc[ai][bj][m][1];
;                     u32x4 w; w.x = cvt_pk(v0[0], v0[1]); w.y = cvt_pk(v0[2], v0[3]); w.z = cvt_pk(v1[0], v1[1]); w.w = cvt_pk(v1[2], v1[3]);
;                     *(GAS u32x4*)(rowp + bj * HALF) = w; } }
	v_lshl_or_b32 v140, s43, 8, v144
	v_lshl_add_u32 v146, s42, 8, v137
	v_ashrrev_i32_e32 v141, 31, v140
	v_lshl_add_u64 v[140:141], v[140:141], 1, s[8:9]
	v_cvt_pk_bf16_f32 v126, v126, v127
	v_cvt_pk_bf16_f32 v127, v128, v129
	v_cvt_pk_bf16_f32 v128, v122, v123
	v_cvt_pk_bf16_f32 v129, v124, v125
	ds_write_b128 v251, v[126:129]
	ds_read_b128 v[126:129], v252
	v_cvt_pk_bf16_f32 v114, v114, v115
	v_cvt_pk_bf16_f32 v115, v116, v117
	v_cvt_pk_bf16_f32 v116, v106, v107
	v_cvt_pk_bf16_f32 v117, v108, v109
	ds_write_b128 v251, v[114:117]
	ds_read_b128 v[114:117], v252
	v_cvt_pk_bf16_f32 v118, v118, v119
	v_cvt_pk_bf16_f32 v119, v120, v121
	v_cvt_pk_bf16_f32 v120, v110, v111
	v_cvt_pk_bf16_f32 v121, v112, v113
	ds_write_b128 v251, v[118:121]
	ds_read_b128 v[118:121], v252
	v_mad_i64_i32 v[254:255], vcc, v146, s5, 0
	v_lshl_add_u64 v[254:255], v[254:255], 1, v[140:141]
	s_waitcnt lgkmcnt(4)
	global_store_dwordx4 v[254:255], v[126:129], off
	v_cvt_pk_bf16_f32 v98, v98, v99
	v_cvt_pk_bf16_f32 v99, v100, v101
	v_cvt_pk_bf16_f32 v100, v90, v91
	v_cvt_pk_bf16_f32 v101, v92, v93
	ds_write_b128 v251, v[98:101]
	ds_read_b128 v[98:101], v252
	s_waitcnt lgkmcnt(4)
	global_store_dwordx4 v[254:255], v[114:117], off offset:256
	v_cvt_pk_bf16_f32 v102, v102, v103
	v_cvt_pk_bf16_f32 v103, v104, v105
	v_cvt_pk_bf16_f32 v104, v94, v95
	v_cvt_pk_bf16_f32 v105, v96, v97
	ds_write_b128 v251, v[102:105]
	ds_read_b128 v[102:105], v252
	v_add_u32_e32 v253, 16, v146
	v_mad_i64_i32 v[254:255], vcc, v253, s5, 0
	v_lshl_add_u64 v[254:255], v[254:255], 1, v[140:141]
	s_waitcnt lgkmcnt(4)
	global_store_dwordx4 v[254:255], v[118:121], off
	v_cvt_pk_bf16_f32 v82, v82, v83
	v_cvt_pk_bf16_f32 v83, v84, v85
	v_cvt_pk_bf16_f32 v84, v74, v75
	v_cvt_pk_bf16_f32 v85, v76, v77
	ds_write_b128 v251, v[82:85]
	ds_read_b128 v[82:85], v252
	s_waitcnt lgkmcnt(4)
	global_store_dwordx4 v[254:255], v[98:101], off offset:256
	v_cvt_pk_bf16_f32 v86, v86, v87
	v_cvt_pk_bf16_f32 v87, v88, v89
	v_cvt_pk_bf16_f32 v88, v78, v79
	v_cvt_pk_bf16_f32 v89, v80, v81
	ds_write_b128 v251, v[86:89]
	ds_read_b128 v[86:89], v252
	v_add_u32_e32 v253, 32, v146
	v_mad_i64_i32 v[254:255], vcc, v253, s5, 0
	v_lshl_add_u64 v[254:255], v[254:255], 1, v[140:141]
	s_waitcnt lgkmcnt(4)
	global_store_dwordx4 v[254:255], v[102:105], off
	v_cvt_pk_bf16_f32 v70, v70, v71
	v_cvt_pk_bf16_f32 v71, v72, v73
	v_cvt_pk_bf16_f32 v72, v66, v67
	v_cvt_pk_bf16_f32 v73, v68, v69
	ds_write_b128 v251, v[70:73]
	ds_read_b128 v[70:73], v252
	s_waitcnt lgkmcnt(4)
	global_store_dwordx4 v[254:255], v[82:85], off offset:256
	v_cvt_pk_bf16_f32 v62, v62, v63
	v_cvt_pk_bf16_f32 v63, v64, v65
	v_cvt_pk_bf16_f32 v64, v58, v59
	v_cvt_pk_bf16_f32 v65, v60, v61
	ds_write_b128 v251, v[62:65]
	ds_read_b128 v[62:65], v252
	v_add_u32_e32 v253, 48, v146
	v_mad_i64_i32 v[254:255], vcc, v253, s5, 0
	v_lshl_add_u64 v[254:255], v[254:255], 1, v[140:141]
	s_waitcnt lgkmcnt(4)
	global_store_dwordx4 v[254:255], v[86:89], off
	v_cvt_pk_bf16_f32 v50, v50, v51
	v_cvt_pk_bf16_f32 v51, v52, v53
	v_cvt_pk_bf16_f32 v52, v42, v43
	v_cvt_pk_bf16_f32 v53, v44, v45
	ds_write_b128 v251, v[50:53]
	ds_read_b128 v[50:53], v252
	s_waitcnt lgkmcnt(4)
	global_store_dwordx4 v[254:255], v[70:73], off offset:256
	v_cvt_pk_bf16_f32 v54, v54, v55
	v_cvt_pk_bf16_f32 v55, v56, v57
	v_cvt_pk_bf16_f32 v56, v46, v47
	v_cvt_pk_bf16_f32 v57, v48, v49
	ds_write_b128 v251, v[54:57]
	ds_read_b128 v[54:57], v252
	v_add_u32_e32 v253, 128, v146
	v_mad_i64_i32 v[254:255], vcc, v253, s5, 0
	v_lshl_add_u64 v[254:255], v[254:255], 1, v[140:141]
	s_waitcnt lgkmcnt(4)
	global_store_dwordx4 v[254:255], v[62:65], off
	v_cvt_pk_bf16_f32 v34, v34, v35
	v_cvt_pk_bf16_f32 v35, v36, v37
	v_cvt_pk_bf16_f32 v36, v26, v27
	v_cvt_pk_bf16_f32 v37, v28, v29
	ds_write_b128 v251, v[34:37]
	ds_read_b128 v[34:37], v252
	s_waitcnt lgkmcnt(4)
	global_store_dwordx4 v[254:255], v[50:53], off offset:256
	v_cvt_pk_bf16_f32 v38, v38, v39
	v_cvt_pk_bf16_f32 v39, v40, v41
	v_cvt_pk_bf16_f32 v40, v30, v31
	v_cvt_pk_bf16_f32 v41, v32, v33
	ds_write_b128 v251, v[38:41]
	ds_read_b128 v[38:41], v252
	v_add_u32_e32 v253, 144, v146
	v_mad_i64_i32 v[254:255], vcc, v253, s5, 0
	v_lshl_add_u64 v[254:255], v[254:255], 1, v[140:141]
	s_waitcnt lgkmcnt(4)
	global_store_dwordx4 v[254:255], v[54:57], off
	v_cvt_pk_bf16_f32 v18, v18, v19
	v_cvt_pk_bf16_f32 v19, v20, v21
	v_cvt_pk_bf16_f32 v20, v10, v11
	v_cvt_pk_bf16_f32 v21, v12, v13
	ds_write_b128 v251, v[18:21]
	ds_read_b128 v[18:21], v252
	s_waitcnt lgkmcnt(4)
	global_store_dwordx4 v[254:255], v[34:37], off offset:256
	v_cvt_pk_bf16_f32 v22, v22, v23
	v_cvt_pk_bf16_f32 v23, v24, v25
	v_cvt_pk_bf16_f32 v24, v14, v15
	v_cvt_pk_bf16_f32 v25, v16, v17
	ds_write_b128 v251, v[22:25]
	ds_read_b128 v[22:25], v252
	v_add_u32_e32 v253, 160, v146
	v_mad_i64_i32 v[254:255], vcc, v253, s5, 0
	v_lshl_add_u64 v[254:255], v[254:255], 1, v[140:141]
	s_waitcnt lgkmcnt(4)
	global_store_dwordx4 v[254:255], v[38:41], off
	v_cvt_pk_bf16_f32 v6, v6, v7
	v_cvt_pk_bf16_f32 v7, v8, v9
	v_cvt_pk_bf16_f32 v8, v2, v3
	v_cvt_pk_bf16_f32 v9, v4, v5
	ds_write_b128 v251, v[6:9]
	ds_read_b128 v[6:9], v252
	s_waitcnt lgkmcnt(4)
	global_store_dwordx4 v[254:255], v[18:21], off offset:256
	v_add_u32_e32 v253, 176, v146
	v_mad_i64_i32 v[254:255], vcc, v253, s5, 0
	v_lshl_add_u64 v[254:255], v[254:255], 1, v[140:141]
	s_waitcnt lgkmcnt(2)
	global_store_dwordx4 v[254:255], v[22:25], off
	s_waitcnt lgkmcnt(0)
	global_store_dwordx4 v[254:255], v[6:9], off offset:256
	s_and_b64 vcc, exec, s[20:21]
	s_mov_b32 s43, s72
	s_mov_b32 s42, s14
	s_mov_b64 s[8:9], s[18:19]
	s_mov_b64 s[26:27], s[10:11]
	s_mov_b64 s[12:13], s[16:17]
	s_mov_b32 s48, 0xffcf4000
	s_movk_i32 s49, 0x3fff
	s_mov_b32 s5, s15
	s_mov_b32 s6, s44
	s_cbranch_vccz .LBB0_148
	s_waitcnt vmcnt(0)
	s_mov_b64 s[46:47], s[80:81]
	s_mov_b32 s45, s97
	s_cmpk_gt_u32 s4, 0xff
	s_cbranch_scc1 .LBB0_169
	s_barrier

; __device__ __forceinline__ int opaque_tid() { int t = threadIdx.x; asm volatile("" : "+v"(t)); return t; }
; #define G_STA(bufoff, gbase, ld) G_STAGE(bufoff, gbase, RA0, RA1, ld)
; #define G_STB(bufoff, gbase, ld) G_STAGE(bufoff, gbase, RB0, RB1, ld)
; #define G_WAIT_V(n) asm volatile("s_waitcnt vmcnt(" #n ")" ::: "memory")
; #define G_BAR __builtin_amdgcn_s_barrier()
; template <bool PERM, class SchedT, class Epi>
; __device__ __forceinline__ void gemm_phase(LAS unsigned char* lds, const SchedT& S, const Epi& E) {
;     const int tid = opaque_tid(), wid = __builtin_amdgcn_readfirstlane(tid >> 6), lane = tid & 63, wr = wid >> 2, wc = wid & 3, fr = lane & 15, fq = lane >> 4;
;     int R0, C0, R1, C1; stage_rc(tid * 16, R0, C0); stage_rc(tid * 16 + 8192, R1, C1);
;     const unsigned RA0 = (unsigned)R0 * 2u, RA1 = (unsigned)R1 * 2u, RB0 = (unsigned)(PERM ? ((R0 & ~31) + perm32(R0 & 31)) : R0) * 2u, RB1 = (unsigned)(PERM ? ((R1 & ~31) + perm32(R1 & 31)) : R1) * 2u;
;     const unsigned CC0 = (unsigned)C0 * 2u, CC1 = (unsigned)C1 * 2u;
;     const size_t kstep = (size_t)(BK * 2);
;     const unsigned ldsw = (unsigned)wid * 1024u;
;     const int aoff = lds_byte(wr * 64 + fr, fq * 8), boff = lds_byte(wc * 32 + fr, fq * 8);
;     ...
;     UnitD cur, nxt; int ui = 0;
;     if (!S.get(0, cur)) return;
;     f32x4 acc[2][2][4][2];
; #pragma unroll
;     for (int a = 0; a < 2; ++a)
; #pragma unroll
;         for (int b = 0; b < 2; ++b)
; #pragma unroll
;             for (int m = 0; m < 4; ++m)
; #pragma unroll
;                 for (int n = 0; n < 2; ++n) acc[a][b][m][n] = (f32x4){0.f, 0.f, 0.f, 0.f};
;     bf16x8 At[4][2], B0[2][2], B1[2][2];
;     const char* cA = cur.A; const char* cB = cur.B;
;     int lda = cur.lda, K = cur.K;
;     ...
;     G_STB(G_SB(0, 0), cB, K); G_STA(G_SA(0, 0), cA, lda); G_STB(G_SB(0, 1), cB + HSTEP(K), K); G_STA(G_SA(0, 1), cA + HSTEP(lda), lda);
;     if (wr == 1) G_BAR;
;     G_WAIT_V(4); G_BAR;
;     G_STB(G_SB(1, 0), cB + kstep, K); G_STA(G_SA(1, 0), cA + kstep, lda); G_STB(G_SB(1, 1), cB + HSTEP(K) + kstep, K);
;     G_WAIT_V(6); G_BAR;
.LBB0_240:
	v_lshl_add_u64 v[10:11], s[18:19], 0, v[0:1]
	v_mov_b32_e32 v131, v1
	s_lshl_b32 s7, s7, 5
	v_lshl_add_u64 v[12:13], s[18:19], 0, v[130:131]
	v_mov_b32_e32 v133, v1
	s_and_b32 s7, s7, 0x60
	v_lshl_add_u64 v[10:11], v[10:11], 0, s[78:79]
	s_add_i32 m0, s22, 0x18000
	v_lshl_add_u64 v[14:15], s[20:21], 0, v[132:133]
	v_mov_b32_e32 v135, v1
	s_lshl_b32 s10, s6, 13
	s_lshl_b32 s11, s7, 7
	s_waitcnt vmcnt(4)
	s_barrier
	global_load_lds_dwordx4 v[10:11], off
	v_lshl_add_u64 v[10:11], v[12:13], 0, s[78:79]
	s_add_i32 m0, s22, 0x1a000
	s_add_i32 s26, s22, 0x8000
	s_add_i32 s27, s22, 0xa000
	v_lshl_add_u64 v[16:17], s[20:21], 0, v[134:135]
	global_load_lds_dwordx4 v[10:11], off
	v_lshl_add_u64 v[10:11], v[14:15], 0, s[78:79]
	s_mov_b32 m0, s26
	s_add_u32 s8, s18, 0x80080
	global_load_lds_dwordx4 v[10:11], off
	v_lshl_add_u64 v[10:11], v[16:17], 0, s[78:79]
	s_mov_b32 m0, s27
	s_addc_u32 s9, s19, 0
	global_load_lds_dwordx4 v[10:11], off
	v_lshl_add_u64 v[10:11], s[8:9], 0, v[0:1]
	s_add_i32 m0, s22, 0x1c000
	v_and_b32_e32 v9, 15, v2
	v_and_b32_e32 v250, 63, v2
	v_lshrrev_b32_e32 v253, 6, v2
	v_lshlrev_b32_e32 v253, 10, v253
	v_add_u32_e32 v253, 0x22000, v253
	v_and_b32_e32 v254, 15, v250
	v_lshrrev_b32_e32 v255, 4, v250
	v_bfe_u32 v251, v254, 1, 2
	v_xor_b32_e32 v251, v251, v255
	v_lshlrev_b32_e32 v251, 4, v251
	v_lshl_add_u32 v251, v254, 6, v251
	v_add_u32_e32 v251, v251, v253
	v_lshrrev_b32_e32 v254, 2, v250
	v_and_b32_e32 v255, 3, v250
	v_bfe_u32 v252, v254, 1, 2
	v_xor_b32_e32 v252, v252, v255
	v_lshlrev_b32_e32 v252, 4, v252
	v_lshl_add_u32 v252, v254, 6, v252
	v_add_u32_e32 v252, v252, v253
	v_lshlrev_b32_e32 v255, 3, v255
	global_load_lds_dwordx4 v[10:11], off
	v_lshl_add_u64 v[10:11], s[8:9], 0, v[130:131]
	s_add_i32 m0, s22, 0x1e000
	v_lshl_or_b32 v146, s6, 6, v9
	v_lshl_or_b32 v250, s6, 6, v254
	global_load_lds_dwordx4 v[10:11], off
	v_lshrrev_b32_e32 v10, 1, v2
	v_and_b32_e32 v10, 24, v10
	v_lshlrev_b32_e32 v11, 1, v10
	v_lshlrev_b32_e32 v2, 2, v2
	v_lshl_or_b32 v9, v9, 6, v11
	v_and_b32_e32 v2, 32, v2
	v_bitop3_b32 v11, v9, s10, v2 bitop3:0xde
	v_bitop3_b32 v147, v9, s11, v2 bitop3:0xde
	v_lshlrev_b32_e32 v2, 15, v3
	v_and_b32_e32 v2, 0xffff0000, v2
	v_lshl_add_u32 v2, v4, 12, v2
	v_and_b32_e32 v3, 1, v3
	v_lshl_or_b32 v2, v3, 6, v2
	v_lshl_add_u32 v136, v6, 1, v2
	v_lshlrev_b32_e32 v2, 15, v5
	v_and_b32_e32 v2, 0xffff0000, v2
	s_waitcnt vmcnt(6)
	v_lshl_add_u32 v2, v7, 12, v2
	v_and_b32_e32 v3, 1, v5
	v_lshl_or_b32 v2, v3, 6, v2
	v_or_b32_e32 v148, s7, v10
	v_or_b32_e32 v255, s7, v255
	v_lshl_or_b32 v250, v250, 16, v255
	s_sub_i32 s28, 0x283f, s7
	v_mov_b32_e32 v137, v1
	v_lshl_add_u32 v138, v8, 1, v2
	v_mov_b32_e32 v139, v1
	s_mov_b32 s29, 0
	v_add_u32_e32 v149, 0, v11
	s_mov_b64 s[14:15], s[20:21]
	s_mov_b64 s[16:17], s[18:19]
	s_barrier
	s_branch .LBB0_242

; #define G_STA(bufoff, gbase, ld) G_STAGE(bufoff, gbase, RA0, RA1, ld)
; #define G_STB(bufoff, gbase, ld) G_STAGE(bufoff, gbase, RB0, RB1, ld)
; #define G_LDA(dst, b, h) do { _Pragma("unroll") for (int m = 0; m < 4; ++m) _Pragma("unroll") for (int k = 0; k < 2; ++k) dst[m][k] = *(const LAS bf16x8*)(lds + G_SA(b, h) + aoff + m * 2048 + k * 1024); } while (0)
; #define G_LDB(dst, b, h) do { _Pragma("unroll") for (int n = 0; n < 2; ++n) _Pragma("unroll") for (int k = 0; k < 2; ++k) dst[n][k] = *(const LAS bf16x8*)(lds + G_SB(b, h) + boff + n * 2048 + k * 1024); } while (0)
; #define G_MMA(ai, bj, At, Bt) do { __builtin_amdgcn_s_setprio(1); _Pragma("unroll") for (int m = 0; m < 4; ++m) _Pragma("unroll") for (int n = 0; n < 2; ++n) _Pragma("unroll") for (int k = 0; k < 2; ++k) \
;         acc[ai][bj][m][n] = __builtin_amdgcn_mfma_f32_16x16x32_bf16(Bt[n][k], At[m][k], acc[ai][bj][m][n], 0, 0, 0); __builtin_amdgcn_s_setprio(0); } while (0)
; #define G_WAIT_L(n) asm volatile("s_waitcnt lgkmcnt(" #n ")" ::: "memory")
; #define G_BAR __builtin_amdgcn_s_barrier()
; #define G_SCHED __builtin_amdgcn_sched_barrier(0)
; template <bool PERM, class SchedT, class Epi>
; __device__ __forceinline__ void gemm_phase(LAS unsigned char* lds, const SchedT& S, const Epi& E) {
;     ...
;         for (int t = 0; t < nt; t += 2) {
;             const bool last = (t == nt - 2);
;             const char* a1 = cA + (size_t)(t + 1) * kstep;
;             const char* a2 = last ? nA : cA + (size_t)(t + 2) * kstep; const char* b2 = last ? nB : cB + (size_t)(t + 2) * kstep;
;             const char* a3 = a2 + kstep; const char* b3 = b2 + kstep;
;             const int wlda = last ? nlda : lda, wK = last ? nK : K;
;             G_LDB(B0, 0, 0); G_SCHED; G_LDA(At, 0, 0); G_STA(G_SA(1, 1), a1 + HSTEP(lda), lda);
;             G_WAIT_L(8); G_BAR; G_WAIT_L(0); G_MMA(0, 0, At, B0); G_BAR; G_SCHED;
;             G_LDB(B1, 0, 1); G_STB(G_SB(0, 0), b2, wK);
;             G_BAR; G_WAIT_L(0); G_MMA(0, 1, At, B1); G_BAR;
;             G_LDA(At, 0, 1); G_STA(G_SA(0, 0), a2, wlda);
;             G_BAR; G_WAIT_L(0); G_MMA(1, 0, At, B0); G_BAR; G_SCHED;
.LBB0_249:
	s_add_u32 s18, s8, 0xfff80080
	s_addc_u32 s19, s9, -1
	s_add_i32 s35, 0, 0x10000
	v_add_u32_e32 v144, s35, v147
	ds_read_b128 v[140:143], v144
	ds_read_b128 v[150:153], v144 offset:1024
	ds_read_b128 v[154:157], v144 offset:2048
	ds_read_b128 v[160:163], v144 offset:3072
	s_cmp_eq_u32 s34, 28
	s_cselect_b32 s21, s15, s19
	s_cselect_b32 s20, s14, s18
	s_cselect_b32 s19, s17, s13
	s_cselect_b32 s18, s16, s11
	v_lshl_add_u64 v[144:145], s[8:9], 0, v[136:137]
	s_add_i32 m0, s22, 0xc000
	ds_read_b128 v[164:167], v149
	ds_read_b128 v[168:171], v149 offset:1024
	ds_read_b128 v[172:175], v149 offset:2048
	ds_read_b128 v[176:179], v149 offset:3072
	ds_read_b128 v[192:195], v149 offset:4096
	ds_read_b128 v[196:199], v149 offset:5120
	ds_read_b128 v[200:203], v149 offset:6144
	ds_read_b128 v[204:207], v149 offset:7168
	global_load_lds_dwordx4 v[144:145], off
	v_lshl_add_u64 v[144:145], s[8:9], 0, v[138:139]
	s_add_i32 m0, s22, 0xe000
	s_nop 0
	global_load_lds_dwordx4 v[144:145], off
	s_waitcnt lgkmcnt(8)
	s_barrier
	s_waitcnt lgkmcnt(0)
	s_setprio 1
	s_waitcnt lgkmcnt(0)
	v_mfma_f32_16x16x32_bf16 v[126:129], v[140:143], v[164:167], v[126:129]
	v_mfma_f32_16x16x32_bf16 v[122:125], v[154:157], v[164:167], v[122:125]
	v_mfma_f32_16x16x32_bf16 v[118:121], v[140:143], v[172:175], v[118:121]
	v_mfma_f32_16x16x32_bf16 v[114:117], v[154:157], v[172:175], v[114:117]
	v_mfma_f32_16x16x32_bf16 v[110:113], v[140:143], v[192:195], v[110:113]
	v_mfma_f32_16x16x32_bf16 v[106:109], v[154:157], v[192:195], v[106:109]
	v_mfma_f32_16x16x32_bf16 v[102:105], v[140:143], v[200:203], v[102:105]
	v_mfma_f32_16x16x32_bf16 v[98:101], v[154:157], v[200:203], v[98:101]
	v_mfma_f32_16x16x32_bf16 v[126:129], v[150:153], v[168:171], v[126:129]
	v_mfma_f32_16x16x32_bf16 v[122:125], v[160:163], v[168:171], v[122:125]
	v_mfma_f32_16x16x32_bf16 v[118:121], v[150:153], v[176:179], v[118:121]
	v_mfma_f32_16x16x32_bf16 v[114:117], v[160:163], v[176:179], v[114:117]
	v_mfma_f32_16x16x32_bf16 v[110:113], v[150:153], v[196:199], v[110:113]
	v_mfma_f32_16x16x32_bf16 v[106:109], v[160:163], v[196:199], v[106:109]
	v_mfma_f32_16x16x32_bf16 v[102:105], v[150:153], v[204:207], v[102:105]
	v_mfma_f32_16x16x32_bf16 v[98:101], v[160:163], v[204:207], v[98:101]
	s_setprio 0
	s_barrier
	s_add_i32 s38, 0, 0x14000
	v_add_u32_e32 v144, s38, v147
	s_add_i32 s35, s35, s5
	ds_read_b128 v[208:211], v144
	ds_read_b128 v[212:215], v144 offset:1024
	ds_read_b128 v[216:219], v144 offset:2048
	ds_read_b128 v[220:223], v144 offset:3072
	v_lshl_add_u64 v[144:145], s[18:19], 0, v[0:1]
	s_mov_b32 m0, s35
	v_lshl_add_u64 v[224:225], s[18:19], 0, v[130:131]
	global_load_lds_dwordx4 v[144:145], off
	s_add_i32 m0, s35, 0x2000
	s_nop 0
	global_load_lds_dwordx4 v[224:225], off
	s_barrier
	s_waitcnt lgkmcnt(0)
	s_setprio 1
	s_waitcnt lgkmcnt(0)
	v_mfma_f32_16x16x32_bf16 v[62:65], v[208:211], v[164:167], v[62:65]
	v_mfma_f32_16x16x32_bf16 v[58:61], v[216:219], v[164:167], v[58:61]
	v_mfma_f32_16x16x32_bf16 v[54:57], v[208:211], v[172:175], v[54:57]
	v_mfma_f32_16x16x32_bf16 v[50:53], v[216:219], v[172:175], v[50:53]
	v_mfma_f32_16x16x32_bf16 v[46:49], v[208:211], v[192:195], v[46:49]
	v_mfma_f32_16x16x32_bf16 v[42:45], v[216:219], v[192:195], v[42:45]
	v_mfma_f32_16x16x32_bf16 v[38:41], v[208:211], v[200:203], v[38:41]
	v_mfma_f32_16x16x32_bf16 v[34:37], v[216:219], v[200:203], v[34:37]
	v_mfma_f32_16x16x32_bf16 v[62:65], v[212:215], v[168:171], v[62:65]
	v_mfma_f32_16x16x32_bf16 v[58:61], v[220:223], v[168:171], v[58:61]
	v_mfma_f32_16x16x32_bf16 v[54:57], v[212:215], v[176:179], v[54:57]
	v_mfma_f32_16x16x32_bf16 v[50:53], v[220:223], v[176:179], v[50:53]
	v_mfma_f32_16x16x32_bf16 v[46:49], v[212:215], v[196:199], v[46:49]
	v_mfma_f32_16x16x32_bf16 v[42:45], v[220:223], v[196:199], v[42:45]
	v_mfma_f32_16x16x32_bf16 v[38:41], v[212:215], v[204:207], v[38:41]
	v_mfma_f32_16x16x32_bf16 v[34:37], v[220:223], v[204:207], v[34:37]
	s_setprio 0
	s_mov_b32 m0, s22
	v_lshl_add_u64 v[230:231], s[20:21], 0, v[132:133]
	s_barrier
	ds_read_b128 v[164:167], v149 offset:16384
	ds_read_b128 v[168:171], v149 offset:17408
	ds_read_b128 v[172:175], v149 offset:18432
	ds_read_b128 v[176:179], v149 offset:19456
	ds_read_b128 v[192:195], v149 offset:20480
	ds_read_b128 v[196:199], v149 offset:21504
	ds_read_b128 v[200:203], v149 offset:22528
	ds_read_b128 v[204:207], v149 offset:23552
	global_load_lds_dwordx4 v[230:231], off
	v_lshl_add_u64 v[232:233], s[20:21], 0, v[134:135]
	s_mov_b32 m0, s23
	s_nop 0
	global_load_lds_dwordx4 v[232:233], off
	s_barrier
	s_waitcnt lgkmcnt(0)
	s_setprio 1
	s_waitcnt lgkmcnt(0)
	v_mfma_f32_16x16x32_bf16 v[94:97], v[140:143], v[164:167], v[94:97]
	v_mfma_f32_16x16x32_bf16 v[90:93], v[154:157], v[164:167], v[90:93]
	v_mfma_f32_16x16x32_bf16 v[86:89], v[140:143], v[172:175], v[86:89]
	v_mfma_f32_16x16x32_bf16 v[82:85], v[154:157], v[172:175], v[82:85]
	v_mfma_f32_16x16x32_bf16 v[78:81], v[140:143], v[192:195], v[78:81]
	v_mfma_f32_16x16x32_bf16 v[74:77], v[154:157], v[192:195], v[74:77]
	v_mfma_f32_16x16x32_bf16 v[70:73], v[140:143], v[200:203], v[70:73]
	v_mfma_f32_16x16x32_bf16 v[66:69], v[154:157], v[200:203], v[66:69]
	v_mfma_f32_16x16x32_bf16 v[94:97], v[150:153], v[168:171], v[94:97]
	v_mfma_f32_16x16x32_bf16 v[90:93], v[160:163], v[168:171], v[90:93]
	v_mfma_f32_16x16x32_bf16 v[86:89], v[150:153], v[176:179], v[86:89]
	v_mfma_f32_16x16x32_bf16 v[82:85], v[160:163], v[176:179], v[82:85]
	v_mfma_f32_16x16x32_bf16 v[78:81], v[150:153], v[196:199], v[78:81]
	v_mfma_f32_16x16x32_bf16 v[74:77], v[160:163], v[196:199], v[74:77]
	v_mfma_f32_16x16x32_bf16 v[70:73], v[150:153], v[204:207], v[70:73]
	v_mfma_f32_16x16x32_bf16 v[66:69], v[160:163], v[204:207], v[66:69]
	s_setprio 0
	s_barrier
; #define G_STA(bufoff, gbase, ld) G_STAGE(bufoff, gbase, RA0, RA1, ld)
; #define G_STB(bufoff, gbase, ld) G_STAGE(bufoff, gbase, RB0, RB1, ld)
; #define G_LDA(dst, b, h) do { _Pragma("unroll") for (int m = 0; m < 4; ++m) _Pragma("unroll") for (int k = 0; k < 2; ++k) dst[m][k] = *(const LAS bf16x8*)(lds + G_SA(b, h) + aoff + m * 2048 + k * 1024); } while (0)
; #define G_LDB(dst, b, h) do { _Pragma("unroll") for (int n = 0; n < 2; ++n) _Pragma("unroll") for (int k = 0; k < 2; ++k) dst[n][k] = *(const LAS bf16x8*)(lds + G_SB(b, h) + boff + n * 2048 + k * 1024); } while (0)
; #define G_MMA(ai, bj, At, Bt) do { __builtin_amdgcn_s_setprio(1); _Pragma("unroll") for (int m = 0; m < 4; ++m) _Pragma("unroll") for (int n = 0; n < 2; ++n) _Pragma("unroll") for (int k = 0; k < 2; ++k) \
;         acc[ai][bj][m][n] = __builtin_amdgcn_mfma_f32_16x16x32_bf16(Bt[n][k], At[m][k], acc[ai][bj][m][n], 0, 0, 0); __builtin_amdgcn_s_setprio(0); } while (0)
; #define G_WAIT_V(n) asm volatile("s_waitcnt vmcnt(" #n ")" ::: "memory")
; #define G_WAIT_L(n) asm volatile("s_waitcnt lgkmcnt(" #n ")" ::: "memory")
; #define G_BAR __builtin_amdgcn_s_barrier()
; #define G_SCHED __builtin_amdgcn_sched_barrier(0)
; template <bool PERM, class SchedT, class Epi>
; __device__ __forceinline__ void gemm_phase(LAS unsigned char* lds, const SchedT& S, const Epi& E) {
;     ...
;             G_STB(G_SB(0, 1), b2 + HSTEP(wK), wK);
;             G_WAIT_V(6); G_BAR; G_MMA(1, 1, At, B1); G_BAR;
;             G_LDB(B0, 1, 0); G_SCHED; G_LDA(At, 1, 0); G_STA(G_SA(0, 1), a2 + HSTEP(wlda), wlda);
;             G_WAIT_L(8); G_BAR; G_WAIT_L(0); G_MMA(0, 0, At, B0); G_BAR; G_SCHED;
;             G_LDB(B1, 1, 1); G_STB(G_SB(1, 0), b3, wK);
;             G_BAR; G_WAIT_L(0); G_MMA(0, 1, At, B1); G_BAR;
;             G_LDA(At, 1, 1); G_STA(G_SA(1, 0), a3, wlda);
;             G_BAR; G_WAIT_L(0); G_MMA(1, 0, At, B0); G_BAR; G_SCHED;
	s_add_u32 s36, s18, 0x80000
	s_addc_u32 s37, s19, 0
	s_add_i32 s35, s38, s5
	v_lshl_add_u64 v[140:141], s[36:37], 0, v[0:1]
	s_mov_b32 m0, s35
	s_nop 0
	global_load_lds_dwordx4 v[140:141], off
	v_lshl_add_u64 v[140:141], s[36:37], 0, v[130:131]
	s_add_i32 m0, s35, 0x2000
	s_nop 0
	global_load_lds_dwordx4 v[140:141], off
	s_waitcnt vmcnt(6)
	s_barrier
	s_setprio 1
	v_mfma_f32_16x16x32_bf16 v[30:33], v[208:211], v[164:167], v[30:33]
	v_mfma_f32_16x16x32_bf16 v[26:29], v[216:219], v[164:167], v[26:29]
	v_mfma_f32_16x16x32_bf16 v[22:25], v[208:211], v[172:175], v[22:25]
	v_mfma_f32_16x16x32_bf16 v[18:21], v[216:219], v[172:175], v[18:21]
	v_mfma_f32_16x16x32_bf16 v[14:17], v[208:211], v[192:195], v[14:17]
	v_mfma_f32_16x16x32_bf16 v[10:13], v[216:219], v[192:195], v[10:13]
	v_mfma_f32_16x16x32_bf16 v[6:9], v[208:211], v[200:203], v[6:9]
	v_mfma_f32_16x16x32_bf16 v[2:5], v[216:219], v[200:203], v[2:5]
	v_mfma_f32_16x16x32_bf16 v[30:33], v[212:215], v[168:171], v[30:33]
	v_mfma_f32_16x16x32_bf16 v[26:29], v[220:223], v[168:171], v[26:29]
	v_mfma_f32_16x16x32_bf16 v[22:25], v[212:215], v[176:179], v[22:25]
	v_mfma_f32_16x16x32_bf16 v[18:21], v[220:223], v[176:179], v[18:21]
	v_mfma_f32_16x16x32_bf16 v[14:17], v[212:215], v[196:199], v[14:17]
	v_mfma_f32_16x16x32_bf16 v[10:13], v[220:223], v[196:199], v[10:13]
	v_mfma_f32_16x16x32_bf16 v[6:9], v[212:215], v[204:207], v[6:9]
	v_mfma_f32_16x16x32_bf16 v[2:5], v[220:223], v[204:207], v[2:5]
	s_setprio 0
	s_add_i32 s35, 0, 0x18000
	v_add_u32_e32 v160, s35, v147
	s_barrier
	ds_read_b128 v[140:143], v160
	ds_read_b128 v[150:153], v160 offset:1024
	ds_read_b128 v[154:157], v160 offset:2048
	ds_read_b128 v[160:163], v160 offset:3072
	s_add_u32 s20, s20, 0x80000
	s_addc_u32 s21, s21, 0
	s_mov_b32 m0, s24
	v_lshl_add_u64 v[208:209], s[20:21], 0, v[132:133]
	ds_read_b128 v[164:167], v149 offset:32768
	ds_read_b128 v[168:171], v149 offset:33792
	ds_read_b128 v[172:175], v149 offset:34816
	ds_read_b128 v[176:179], v149 offset:35840
	ds_read_b128 v[192:195], v149 offset:36864
	ds_read_b128 v[196:199], v149 offset:37888
	ds_read_b128 v[200:203], v149 offset:38912
	ds_read_b128 v[204:207], v149 offset:39936
	global_load_lds_dwordx4 v[208:209], off
	v_lshl_add_u64 v[208:209], s[20:21], 0, v[134:135]
	s_mov_b32 m0, s25
	s_nop 0
	global_load_lds_dwordx4 v[208:209], off
	s_waitcnt lgkmcnt(8)
	s_barrier
	s_waitcnt lgkmcnt(0)
	s_setprio 1
	s_waitcnt lgkmcnt(0)
	v_mfma_f32_16x16x32_bf16 v[126:129], v[140:143], v[164:167], v[126:129]
	v_mfma_f32_16x16x32_bf16 v[122:125], v[154:157], v[164:167], v[122:125]
	v_mfma_f32_16x16x32_bf16 v[118:121], v[140:143], v[172:175], v[118:121]
	v_mfma_f32_16x16x32_bf16 v[114:117], v[154:157], v[172:175], v[114:117]
	v_mfma_f32_16x16x32_bf16 v[110:113], v[140:143], v[192:195], v[110:113]
	v_mfma_f32_16x16x32_bf16 v[106:109], v[154:157], v[192:195], v[106:109]
	v_mfma_f32_16x16x32_bf16 v[102:105], v[140:143], v[200:203], v[102:105]
	v_mfma_f32_16x16x32_bf16 v[98:101], v[154:157], v[200:203], v[98:101]
	v_mfma_f32_16x16x32_bf16 v[126:129], v[150:153], v[168:171], v[126:129]
	v_mfma_f32_16x16x32_bf16 v[122:125], v[160:163], v[168:171], v[122:125]
	v_mfma_f32_16x16x32_bf16 v[118:121], v[150:153], v[176:179], v[118:121]
	v_mfma_f32_16x16x32_bf16 v[114:117], v[160:163], v[176:179], v[114:117]
	v_mfma_f32_16x16x32_bf16 v[110:113], v[150:153], v[196:199], v[110:113]
	v_mfma_f32_16x16x32_bf16 v[106:109], v[160:163], v[196:199], v[106:109]
	v_mfma_f32_16x16x32_bf16 v[102:105], v[150:153], v[204:207], v[102:105]
	v_mfma_f32_16x16x32_bf16 v[98:101], v[160:163], v[204:207], v[98:101]
	s_setprio 0
	s_barrier
	s_add_i32 s20, 0, 0x1c000
	s_add_i32 s21, s35, s5
	v_add_u32_e32 v220, s20, v147
	v_lshl_add_u64 v[144:145], v[144:145], 0, s[78:79]
	s_mov_b32 m0, s21
	ds_read_b128 v[208:211], v220
	ds_read_b128 v[212:215], v220 offset:1024
	ds_read_b128 v[216:219], v220 offset:2048
	ds_read_b128 v[220:223], v220 offset:3072
	global_load_lds_dwordx4 v[144:145], off
	v_lshl_add_u64 v[144:145], v[224:225], 0, s[78:79]
	s_add_i32 m0, s21, 0x2000
	s_nop 0
	global_load_lds_dwordx4 v[144:145], off
	s_barrier
	s_waitcnt lgkmcnt(0)
	s_setprio 1
	s_waitcnt lgkmcnt(0)
	v_mfma_f32_16x16x32_bf16 v[62:65], v[208:211], v[164:167], v[62:65]
	v_mfma_f32_16x16x32_bf16 v[58:61], v[216:219], v[164:167], v[58:61]
	v_mfma_f32_16x16x32_bf16 v[54:57], v[208:211], v[172:175], v[54:57]
	v_mfma_f32_16x16x32_bf16 v[50:53], v[216:219], v[172:175], v[50:53]
	v_mfma_f32_16x16x32_bf16 v[46:49], v[208:211], v[192:195], v[46:49]
	v_mfma_f32_16x16x32_bf16 v[42:45], v[216:219], v[192:195], v[42:45]
	v_mfma_f32_16x16x32_bf16 v[38:41], v[208:211], v[200:203], v[38:41]
	v_mfma_f32_16x16x32_bf16 v[34:37], v[216:219], v[200:203], v[34:37]
	v_mfma_f32_16x16x32_bf16 v[62:65], v[212:215], v[168:171], v[62:65]
	v_mfma_f32_16x16x32_bf16 v[58:61], v[220:223], v[168:171], v[58:61]
	v_mfma_f32_16x16x32_bf16 v[54:57], v[212:215], v[176:179], v[54:57]
	v_mfma_f32_16x16x32_bf16 v[50:53], v[220:223], v[176:179], v[50:53]
	v_mfma_f32_16x16x32_bf16 v[46:49], v[212:215], v[196:199], v[46:49]
	v_mfma_f32_16x16x32_bf16 v[42:45], v[220:223], v[196:199], v[42:45]
	v_mfma_f32_16x16x32_bf16 v[38:41], v[212:215], v[204:207], v[38:41]
	v_mfma_f32_16x16x32_bf16 v[34:37], v[220:223], v[204:207], v[34:37]
	s_setprio 0
	s_mov_b32 m0, s26
	v_lshl_add_u64 v[144:145], v[230:231], 0, s[78:79]
	s_barrier
	ds_read_b128 v[164:167], v149 offset:49152
	ds_read_b128 v[168:171], v149 offset:50176
	ds_read_b128 v[172:175], v149 offset:51200
	ds_read_b128 v[176:179], v149 offset:52224
	ds_read_b128 v[192:195], v149 offset:53248
	ds_read_b128 v[196:199], v149 offset:54272
	ds_read_b128 v[200:203], v149 offset:55296
	ds_read_b128 v[204:207], v149 offset:56320
	global_load_lds_dwordx4 v[144:145], off
	v_lshl_add_u64 v[144:145], v[232:233], 0, s[78:79]
	s_mov_b32 m0, s27
	s_nop 0
	global_load_lds_dwordx4 v[144:145], off
	s_barrier
; #define G_STA(bufoff, gbase, ld) G_STAGE(bufoff, gbase, RA0, RA1, ld)
; #define G_STB(bufoff, gbase, ld) G_STAGE(bufoff, gbase, RB0, RB1, ld)
; #define G_LDA(dst, b, h) do { _Pragma("unroll") for (int m = 0; m < 4; ++m) _Pragma("unroll") for (int k = 0; k < 2; ++k) dst[m][k] = *(const LAS bf16x8*)(lds + G_SA(b, h) + aoff + m * 2048 + k * 1024); } while (0)
; #define G_LDB(dst, b, h) do { _Pragma("unroll") for (int n = 0; n < 2; ++n) _Pragma("unroll") for (int k = 0; k < 2; ++k) dst[n][k] = *(const LAS bf16x8*)(lds + G_SB(b, h) + boff + n * 2048 + k * 1024); } while (0)
; #define G_MMA(ai, bj, At, Bt) do { __builtin_amdgcn_s_setprio(1); _Pragma("unroll") for (int m = 0; m < 4; ++m) _Pragma("unroll") for (int n = 0; n < 2; ++n) _Pragma("unroll") for (int k = 0; k < 2; ++k) \
;         acc[ai][bj][m][n] = __builtin_amdgcn_mfma_f32_16x16x32_bf16(Bt[n][k], At[m][k], acc[ai][bj][m][n], 0, 0, 0); __builtin_amdgcn_s_setprio(0); } while (0)
; #define G_WAIT_V(n) asm volatile("s_waitcnt vmcnt(" #n ")" ::: "memory")
; #define G_WAIT_L(n) asm volatile("s_waitcnt lgkmcnt(" #n ")" ::: "memory")
; #define G_BAR __builtin_amdgcn_s_barrier()
; #define G_SCHED __builtin_amdgcn_sched_barrier(0)
; template <bool PERM, class SchedT, class Epi>
; __device__ __forceinline__ void gemm_phase(LAS unsigned char* lds, const SchedT& S, const Epi& E) {
;     ...
;             G_WAIT_L(8); G_BAR; G_WAIT_L(0); G_MMA(0, 0, At, B0); G_BAR; G_SCHED;
;             G_LDB(B1, 1, 1); G_STB(G_SB(1, 0), b3, wK);
;             G_BAR; G_WAIT_L(0); G_MMA(0, 1, At, B1); G_BAR;
;             G_LDA(At, 1, 1); G_STA(G_SA(1, 0), a3, wlda);
;             G_BAR; G_WAIT_L(0); G_MMA(1, 0, At, B0); G_BAR; G_SCHED;
;             G_STB(G_SB(1, 1), b3 + HSTEP(wK), wK);
;             G_WAIT_V(6); G_BAR; G_MMA(1, 1, At, B1); G_BAR;
;         }
;     __device__ __forceinline__ void operator()(const f32x4 (&acc)[2][2][4][2], const UnitD& u, int wr, int wc, int fr, int fq) const {
;     ...
;             const bool gate = (u.pn * BM + bj * HALF + wc * 32) >= C_G;
	s_waitcnt lgkmcnt(0)
	s_setprio 1
	s_waitcnt lgkmcnt(0)
	v_mfma_f32_16x16x32_bf16 v[94:97], v[140:143], v[164:167], v[94:97]
	v_mfma_f32_16x16x32_bf16 v[90:93], v[154:157], v[164:167], v[90:93]
	v_mfma_f32_16x16x32_bf16 v[86:89], v[140:143], v[172:175], v[86:89]
	v_mfma_f32_16x16x32_bf16 v[82:85], v[154:157], v[172:175], v[82:85]
	v_mfma_f32_16x16x32_bf16 v[78:81], v[140:143], v[192:195], v[78:81]
	v_mfma_f32_16x16x32_bf16 v[74:77], v[154:157], v[192:195], v[74:77]
	v_mfma_f32_16x16x32_bf16 v[70:73], v[140:143], v[200:203], v[70:73]
	v_mfma_f32_16x16x32_bf16 v[66:69], v[154:157], v[200:203], v[66:69]
	v_mfma_f32_16x16x32_bf16 v[94:97], v[150:153], v[168:171], v[94:97]
	v_mfma_f32_16x16x32_bf16 v[90:93], v[160:163], v[168:171], v[90:93]
	v_mfma_f32_16x16x32_bf16 v[86:89], v[150:153], v[176:179], v[86:89]
	v_mfma_f32_16x16x32_bf16 v[82:85], v[160:163], v[176:179], v[82:85]
	v_mfma_f32_16x16x32_bf16 v[78:81], v[150:153], v[196:199], v[78:81]
	v_mfma_f32_16x16x32_bf16 v[74:77], v[160:163], v[196:199], v[74:77]
	v_mfma_f32_16x16x32_bf16 v[70:73], v[150:153], v[204:207], v[70:73]
	v_mfma_f32_16x16x32_bf16 v[66:69], v[160:163], v[204:207], v[66:69]
	s_setprio 0
	s_barrier
	s_add_u32 s18, s18, 0x80080
	s_addc_u32 s19, s19, 0
	s_add_i32 s20, s20, s5
	v_lshl_add_u64 v[140:141], s[18:19], 0, v[0:1]
	s_mov_b32 m0, s20
	s_nop 0
	global_load_lds_dwordx4 v[140:141], off
	v_lshl_add_u64 v[140:141], s[18:19], 0, v[130:131]
	s_add_i32 m0, s20, 0x2000
	s_nop 0
	global_load_lds_dwordx4 v[140:141], off
	s_waitcnt vmcnt(6)
	s_barrier
	s_setprio 1
	v_mfma_f32_16x16x32_bf16 v[30:33], v[208:211], v[164:167], v[30:33]
	v_mfma_f32_16x16x32_bf16 v[26:29], v[216:219], v[164:167], v[26:29]
	v_mfma_f32_16x16x32_bf16 v[22:25], v[208:211], v[172:175], v[22:25]
	v_mfma_f32_16x16x32_bf16 v[18:21], v[216:219], v[172:175], v[18:21]
	v_mfma_f32_16x16x32_bf16 v[14:17], v[208:211], v[192:195], v[14:17]
	v_mfma_f32_16x16x32_bf16 v[10:13], v[216:219], v[192:195], v[10:13]
	v_mfma_f32_16x16x32_bf16 v[6:9], v[208:211], v[200:203], v[6:9]
	v_mfma_f32_16x16x32_bf16 v[2:5], v[216:219], v[200:203], v[2:5]
	v_mfma_f32_16x16x32_bf16 v[30:33], v[212:215], v[168:171], v[30:33]
	v_mfma_f32_16x16x32_bf16 v[26:29], v[220:223], v[168:171], v[26:29]
	v_mfma_f32_16x16x32_bf16 v[22:25], v[212:215], v[176:179], v[22:25]
	v_mfma_f32_16x16x32_bf16 v[18:21], v[220:223], v[176:179], v[18:21]
	v_mfma_f32_16x16x32_bf16 v[14:17], v[212:215], v[196:199], v[14:17]
	v_mfma_f32_16x16x32_bf16 v[10:13], v[220:223], v[196:199], v[10:13]
	v_mfma_f32_16x16x32_bf16 v[6:9], v[212:215], v[204:207], v[6:9]
	v_mfma_f32_16x16x32_bf16 v[2:5], v[220:223], v[204:207], v[2:5]
	s_setprio 0
	s_add_i32 s34, s34, 2
	s_add_u32 s8, s8, 0x100
	s_addc_u32 s9, s9, 0
	s_add_u32 s11, s11, 0x100
	s_addc_u32 s13, s13, 0
	s_cmp_gt_u32 s34, 29
	s_barrier
	s_cbranch_scc0 .LBB0_249
	s_cmpk_lt_u32 s31, 0x28
	s_cbranch_scc0 .Lg1_slow
; __device__ __forceinline__ unsigned cvt_pk(float lo, float hi) { unsigned r; asm volatile("v_cvt_pk_bf16_f32 %0, %1, %2" : "=v"(r) : "v"(lo), "v"(hi)); return r; }
; __device__ __forceinline__ float sigm(float x) { return __builtin_amdgcn_rcpf(1.f + __expf(-x)); }
; #define GAS __attribute__((address_space(1)))
;     __device__ __forceinline__ void operator()(const f32x4 (&acc)[2][2][4][2], const UnitD& u, int wr, int wc, int fr, int fq) const {
;         const int row0 = u.pm * BM + wr * 64 + fr, col0 = u.pn * BM + wc * 32 + 8 * fq;
;         GAS bf16_t* C = (GAS bf16_t*)(unsigned long long)u.C;
; #pragma unroll
;         for (int bj = 0; bj < 2; ++bj) {
;             const bool gate = (u.pn * BM + bj * HALF + wc * 32) >= C_G;
; #pragma unroll
;             for (int ai = 0; ai < 2; ++ai)
; #pragma unroll
;                 for (int m = 0; m < 4; ++m) { GAS bf16_t* rowp = C + (size_t)(row0 + ai * HALF + m * 16) * NP;
;                     const f32x4 v0 = acc[ai][bj][m][0], v1 = acc[ai][bj][m][1];
;                     if (!gate) { u32x4 w; w.x = cvt_pk(v0[0], v0[1]); w.y = cvt_pk(v0[2], v0[3]); w.z = cvt_pk(v1[0], v1[1]); w.w = cvt_pk(v1[2], v1[3]);
;                         *(GAS u32x4*)(rowp + col0 + bj * HALF) = w; }
;                     else { unsigned b[8];
; #pragma unroll
;                         for (int j = 0; j < 4; ++j) { b[j] = (unsigned)(sigm(v0[j]) * 255.f + 0.5f); b[4 + j] = (unsigned)(sigm(v1[j]) * 255.f + 0.5f); }
;                         u32x2 w; w.x = b[0] | (b[1] << 8) | (b[2] << 16) | (b[3] << 24); w.y = b[4] | (b[5] << 8) | (b[6] << 16) | (b[7] << 24);
;                         *(GAS u32x2*)((GAS unsigned char*)(rowp + C_G) + (col0 + bj * HALF - C_G)) = w; } }
	v_readlane_b32 s8, v249, 2
	v_readlane_b32 s9, v249, 3
	s_lshl_b32 s11, s31, 8
	v_lshrrev_b32_e32 v253, 16, v250
	v_and_b32_e32 v254, 0xff, v250
	v_lshl_add_u32 v150, s30, 8, v253
	v_or_b32_e32 v144, s11, v254
	v_ashrrev_i32_e32 v145, 31, v144
	v_lshl_add_u64 v[140:141], v[144:145], 1, s[8:9]
	v_cvt_pk_bf16_f32 v126, v126, v127
	v_cvt_pk_bf16_f32 v127, v128, v129
	v_cvt_pk_bf16_f32 v128, v122, v123
	v_cvt_pk_bf16_f32 v129, v124, v125
	ds_write_b128 v251, v[126:129]
	ds_read_b128 v[126:129], v252
	v_cvt_pk_bf16_f32 v62, v62, v63
	v_cvt_pk_bf16_f32 v63, v64, v65
	v_cvt_pk_bf16_f32 v64, v58, v59
	v_cvt_pk_bf16_f32 v65, v60, v61
	ds_write_b128 v251, v[62:65]
	ds_read_b128 v[62:65], v252
	v_cvt_pk_bf16_f32 v118, v118, v119
	v_cvt_pk_bf16_f32 v119, v120, v121
	v_cvt_pk_bf16_f32 v120, v114, v115
	v_cvt_pk_bf16_f32 v121, v116, v117
	ds_write_b128 v251, v[118:121]
	ds_read_b128 v[118:121], v252
	v_mad_i64_i32 v[254:255], vcc, v150, s3, 0
	v_lshl_add_u64 v[254:255], v[254:255], 0, v[140:141]
	s_waitcnt lgkmcnt(4)
	global_store_dwordx4 v[254:255], v[126:129], off
	v_cvt_pk_bf16_f32 v54, v54, v55
	v_cvt_pk_bf16_f32 v55, v56, v57
	v_cvt_pk_bf16_f32 v56, v50, v51
	v_cvt_pk_bf16_f32 v57, v52, v53
	ds_write_b128 v251, v[54:57]
	ds_read_b128 v[54:57], v252
	s_waitcnt lgkmcnt(4)
	global_store_dwordx4 v[254:255], v[62:65], off offset:256
	v_cvt_pk_bf16_f32 v110, v110, v111
	v_cvt_pk_bf16_f32 v111, v112, v113
	v_cvt_pk_bf16_f32 v112, v106, v107
	v_cvt_pk_bf16_f32 v113, v108, v109
	ds_write_b128 v251, v[110:113]
	ds_read_b128 v[110:113], v252
	v_add_u32_e32 v253, 16, v150
	v_mad_i64_i32 v[254:255], vcc, v253, s3, 0
	v_lshl_add_u64 v[254:255], v[254:255], 0, v[140:141]
	s_waitcnt lgkmcnt(4)
	global_store_dwordx4 v[254:255], v[118:121], off
	v_cvt_pk_bf16_f32 v46, v46, v47
	v_cvt_pk_bf16_f32 v47, v48, v49
	v_cvt_pk_bf16_f32 v48, v42, v43
	v_cvt_pk_bf16_f32 v49, v44, v45
	ds_write_b128 v251, v[46:49]
	ds_read_b128 v[46:49], v252
	s_waitcnt lgkmcnt(4)
	global_store_dwordx4 v[254:255], v[54:57], off offset:256
	v_cvt_pk_bf16_f32 v102, v102, v103
	v_cvt_pk_bf16_f32 v103, v104, v105
	v_cvt_pk_bf16_f32 v104, v98, v99
	v_cvt_pk_bf16_f32 v105, v100, v101
	ds_write_b128 v251, v[102:105]
	ds_read_b128 v[102:105], v252
	v_add_u32_e32 v253, 32, v150
	v_mad_i64_i32 v[254:255], vcc, v253, s3, 0
	v_lshl_add_u64 v[254:255], v[254:255], 0, v[140:141]
	s_waitcnt lgkmcnt(4)
	global_store_dwordx4 v[254:255], v[110:113], off
	v_cvt_pk_bf16_f32 v38, v38, v39
	v_cvt_pk_bf16_f32 v39, v40, v41
	v_cvt_pk_bf16_f32 v40, v34, v35
	v_cvt_pk_bf16_f32 v41, v36, v37
	ds_write_b128 v251, v[38:41]
	ds_read_b128 v[38:41], v252
	s_waitcnt lgkmcnt(4)
	global_store_dwordx4 v[254:255], v[46:49], off offset:256
	v_cvt_pk_bf16_f32 v94, v94, v95
	v_cvt_pk_bf16_f32 v95, v96, v97
	v_cvt_pk_bf16_f32 v96, v90, v91
	v_cvt_pk_bf16_f32 v97, v92, v93
	ds_write_b128 v251, v[94:97]
	ds_read_b128 v[94:97], v252
	v_add_u32_e32 v253, 48, v150
	v_mad_i64_i32 v[254:255], vcc, v253, s3, 0
	v_lshl_add_u64 v[254:255], v[254:255], 0, v[140:141]
	s_waitcnt lgkmcnt(4)
	global_store_dwordx4 v[254:255], v[102:105], off
	v_cvt_pk_bf16_f32 v30, v30, v31
	v_cvt_pk_bf16_f32 v31, v32, v33
	v_cvt_pk_bf16_f32 v32, v26, v27
	v_cvt_pk_bf16_f32 v33, v28, v29
	ds_write_b128 v251, v[30:33]
	ds_read_b128 v[30:33], v252
	s_waitcnt lgkmcnt(4)
	global_store_dwordx4 v[254:255], v[38:41], off offset:256
	v_cvt_pk_bf16_f32 v86, v86, v87
	v_cvt_pk_bf16_f32 v87, v88, v89
	v_cvt_pk_bf16_f32 v88, v82, v83
	v_cvt_pk_bf16_f32 v89, v84, v85
	ds_write_b128 v251, v[86:89]
	ds_read_b128 v[86:89], v252
	v_add_u32_e32 v253, 128, v150
	v_mad_i64_i32 v[254:255], vcc, v253, s3, 0
	v_lshl_add_u64 v[254:255], v[254:255], 0, v[140:141]
	s_waitcnt lgkmcnt(4)
	global_store_dwordx4 v[254:255], v[94:97], off
	v_cvt_pk_bf16_f32 v22, v22, v23
	v_cvt_pk_bf16_f32 v23, v24, v25
	v_cvt_pk_bf16_f32 v24, v18, v19
	v_cvt_pk_bf16_f32 v25, v20, v21
	ds_write_b128 v251, v[22:25]
	ds_read_b128 v[22:25], v252
	s_waitcnt lgkmcnt(4)
	global_store_dwordx4 v[254:255], v[30:33], off offset:256
	v_cvt_pk_bf16_f32 v78, v78, v79
	v_cvt_pk_bf16_f32 v79, v80, v81
	v_cvt_pk_bf16_f32 v80, v74, v75
	v_cvt_pk_bf16_f32 v81, v76, v77
	ds_write_b128 v251, v[78:81]
	ds_read_b128 v[78:81], v252
	v_add_u32_e32 v253, 144, v150
	v_mad_i64_i32 v[254:255], vcc, v253, s3, 0
	v_lshl_add_u64 v[254:255], v[254:255], 0, v[140:141]
	s_waitcnt lgkmcnt(4)
	global_store_dwordx4 v[254:255], v[86:89], off
	v_cvt_pk_bf16_f32 v14, v14, v15
	v_cvt_pk_bf16_f32 v15, v16, v17
	v_cvt_pk_bf16_f32 v16, v10, v11
	v_cvt_pk_bf16_f32 v17, v12, v13
	ds_write_b128 v251, v[14:17]
	ds_read_b128 v[14:17], v252
	s_waitcnt lgkmcnt(4)
	global_store_dwordx4 v[254:255], v[22:25], off offset:256
	v_cvt_pk_bf16_f32 v70, v70, v71
	v_cvt_pk_bf16_f32 v71, v72, v73
	v_cvt_pk_bf16_f32 v72, v66, v67
	v_cvt_pk_bf16_f32 v73, v68, v69
	ds_write_b128 v251, v[70:73]
	ds_read_b128 v[70:73], v252
	v_add_u32_e32 v253, 160, v150
	v_mad_i64_i32 v[254:255], vcc, v253, s3, 0
	v_lshl_add_u64 v[254:255], v[254:255], 0, v[140:141]
	s_waitcnt lgkmcnt(4)
	global_store_dwordx4 v[254:255], v[78:81], off
	v_cvt_pk_bf16_f32 v6, v6, v7
	v_cvt_pk_bf16_f32 v7, v8, v9
	v_cvt_pk_bf16_f32 v8, v2, v3
	v_cvt_pk_bf16_f32 v9, v4, v5
	ds_write_b128 v251, v[6:9]
	ds_read_b128 v[6:9], v252
	s_waitcnt lgkmcnt(4)
	global_store_dwordx4 v[254:255], v[14:17], off offset:256
	v_add_u32_e32 v253, 176, v150
	v_mad_i64_i32 v[254:255], vcc, v253, s3, 0
	v_lshl_add_u64 v[254:255], v[254:255], 0, v[140:141]
	s_waitcnt lgkmcnt(2)
	global_store_dwordx4 v[254:255], v[70:73], off
	s_waitcnt lgkmcnt(0)
	global_store_dwordx4 v[254:255], v[6:9], off offset:256
	s_branch .LBB0_241
.Lg1_slow:
	s_lshl_b32 s11, s31, 8
	v_lshl_add_u32 v150, s30, 8, v146
	v_readlane_b32 s30, v249, 2
	v_readlane_b32 s31, v249, 3
	v_or_b32_e32 v144, s11, v148
	s_cmp_le_i32 s11, s28
	v_mov_b64_e32 v[140:141], s[30:31]
	v_ashrrev_i32_e32 v145, 31, v144
	s_cselect_b64 s[18:19], -1, 0
	v_mad_i64_i32 v[140:141], s[8:9], v150, s3, v[140:141]
	s_mov_b64 s[8:9], -1
	s_and_b64 vcc, exec, s[18:19]
	v_lshl_add_u64 v[142:143], v[144:145], 1, v[140:141]
	s_cbranch_vccz .LBB0_252
	v_cvt_pk_bf16_f32 v152, v126, v127
	v_cvt_pk_bf16_f32 v153, v128, v129
	v_cvt_pk_bf16_f32 v154, v122, v123
	v_cvt_pk_bf16_f32 v155, v124, v125
	global_store_dwordx4 v[142:143], v[152:155], off
	s_mov_b64 s[8:9], 0

; __device__ __forceinline__ int opaque_tid() { int t = threadIdx.x; asm volatile("" : "+v"(t)); return t; }
; #define G_STA(bufoff, gbase, ld) G_STAGE(bufoff, gbase, RA0, RA1, ld)
; #define G_STB(bufoff, gbase, ld) G_STAGE(bufoff, gbase, RB0, RB1, ld)
; #define G_WAIT_V(n) asm volatile("s_waitcnt vmcnt(" #n ")" ::: "memory")
; #define G_BAR __builtin_amdgcn_s_barrier()
; template <bool PERM, class SchedT, class Epi>
; __device__ __forceinline__ void gemm_phase(LAS unsigned char* lds, const SchedT& S, const Epi& E) {
;     const int tid = opaque_tid(), wid = __builtin_amdgcn_readfirstlane(tid >> 6), lane = tid & 63, wr = wid >> 2, wc = wid & 3, fr = lane & 15, fq = lane >> 4;
;     int R0, C0, R1, C1; stage_rc(tid * 16, R0, C0); stage_rc(tid * 16 + 8192, R1, C1);
;     const unsigned RA0 = (unsigned)R0 * 2u, RA1 = (unsigned)R1 * 2u, RB0 = (unsigned)(PERM ? ((R0 & ~31) + perm32(R0 & 31)) : R0) * 2u, RB1 = (unsigned)(PERM ? ((R1 & ~31) + perm32(R1 & 31)) : R1) * 2u;
;     const unsigned CC0 = (unsigned)C0 * 2u, CC1 = (unsigned)C1 * 2u;
;     const size_t kstep = (size_t)(BK * 2);
;     const unsigned ldsw = (unsigned)wid * 1024u;
;     const int aoff = lds_byte(wr * 64 + fr, fq * 8), boff = lds_byte(wc * 32 + fr, fq * 8);
;     ...
;     UnitD cur, nxt; int ui = 0;
;     if (!S.get(0, cur)) return;
;     f32x4 acc[2][2][4][2];
; #pragma unroll
;     for (int a = 0; a < 2; ++a)
; #pragma unroll
;         for (int b = 0; b < 2; ++b)
; #pragma unroll
;             for (int m = 0; m < 4; ++m)
; #pragma unroll
;                 for (int n = 0; n < 2; ++n) acc[a][b][m][n] = (f32x4){0.f, 0.f, 0.f, 0.f};
;     bf16x8 At[4][2], B0[2][2], B1[2][2];
;     const char* cA = cur.A; const char* cB = cur.B;
;     int lda = cur.lda, K = cur.K;
;     ...
;     G_STB(G_SB(0, 0), cB, K); G_STA(G_SA(0, 0), cA, lda); G_STB(G_SB(0, 1), cB + HSTEP(K), K); G_STA(G_SA(0, 1), cA + HSTEP(lda), lda);
;     if (wr == 1) G_BAR;
;     G_WAIT_V(4); G_BAR;
;     G_STB(G_SB(1, 0), cB + kstep, K); G_STA(G_SA(1, 0), cA + kstep, lda); G_STB(G_SB(1, 1), cB + HSTEP(K) + kstep, K);
;     G_WAIT_V(6); G_BAR;
;     __device__ __forceinline__ void operator()(f32x4 (&acc)[2][2][4][2], const UnitD& u, int wr, int wc, int fr, int fq) const {
;         const int row0 = u.pm * BM + wr * 64 + fr, col0 = u.pn * BM + wc * 32 + 4 * fq;
.LBB0_358:
	v_and_b32_e32 v250, 63, v8
	v_lshrrev_b32_e32 v253, 6, v8
	v_lshlrev_b32_e32 v253, 10, v253
	v_add_u32_e32 v253, 0x22000, v253
	v_and_b32_e32 v254, 15, v250
	v_lshrrev_b32_e32 v255, 4, v250
	v_bfe_u32 v251, v254, 1, 2
	v_xor_b32_e32 v251, v251, v255
	v_lshlrev_b32_e32 v251, 4, v251
	v_lshl_add_u32 v251, v254, 6, v251
	v_add_u32_e32 v251, v251, v253
	v_lshrrev_b32_e32 v254, 2, v250
	v_and_b32_e32 v255, 3, v250
	v_bfe_u32 v252, v254, 1, 2
	v_xor_b32_e32 v252, v252, v255
	v_lshlrev_b32_e32 v252, 4, v252
	v_lshl_add_u32 v252, v254, 6, v252
	v_add_u32_e32 v252, v252, v253
	v_lshlrev_b32_e32 v255, 3, v255
	v_bfe_u32 v18, v8, 4, 2
	v_readlane_b32 s26, v248, 40
	v_and_b32_e32 v9, 15, v8
	v_lshlrev_b32_e32 v19, 4, v18
	v_lshlrev_b32_e32 v8, 2, v8
	s_lshl_b32 s14, s14, 5
	v_readlane_b32 s27, v248, 41
	v_lshl_or_b32 v154, s15, 6, v254
	v_lshl_or_b32 v9, v9, 6, v19
	s_lshl_b32 s15, s15, 13
	v_and_b32_e32 v8, 32, v8
	s_and_b32 s14, s14, 0x60
	v_lshl_add_u64 v[10:11], s[26:27], 0, v[0:1]
	v_mov_b32_e32 v131, v1
	v_readlane_b32 s24, v248, 36
	v_bitop3_b32 v19, v9, s15, v8 bitop3:0xde
	s_lshl_b32 s15, s14, 7
	v_lshl_add_u64 v[12:13], s[26:27], 0, v[130:131]
	v_readlane_b32 s25, v248, 37
	v_bitop3_b32 v155, v9, s15, v8 bitop3:0xde
	v_lshl_add_u64 v[8:9], v[10:11], 0, s[78:79]
	s_add_i32 m0, s30, 0x18000
	v_lshl_add_u64 v[14:15], s[24:25], 0, v[0:1]
	s_waitcnt vmcnt(4)
	s_barrier
	global_load_lds_dwordx4 v[8:9], off
	v_lshl_add_u64 v[8:9], v[12:13], 0, s[78:79]
	s_add_i32 m0, s30, 0x1a000
	s_add_i32 s36, s30, 0x8000
	v_lshl_add_u64 v[16:17], s[24:25], 0, v[130:131]
	global_load_lds_dwordx4 v[8:9], off
	v_lshl_add_u64 v[8:9], v[14:15], 0, s[78:79]
	s_mov_b32 m0, s36
	s_add_i32 s37, s30, 0xa000
	v_readlane_b32 s16, v248, 42
	global_load_lds_dwordx4 v[8:9], off
	v_lshl_add_u64 v[8:9], v[16:17], 0, s[78:79]
	s_mov_b32 m0, s37
	v_readlane_b32 s17, v248, 43
	global_load_lds_dwordx4 v[8:9], off
	s_nop 0
	v_lshl_add_u64 v[8:9], s[16:17], 0, v[0:1]
	s_add_i32 m0, s30, 0x1c000
	v_lshrrev_b32_e32 v255, 1, v255
	v_or_b32_e32 v156, s14, v255
	global_load_lds_dwordx4 v[8:9], off
	v_lshl_add_u64 v[8:9], s[16:17], 0, v[130:131]
	s_add_i32 m0, s30, 0x1e000
	v_readlane_b32 s14, v248, 30
	global_load_lds_dwordx4 v[8:9], off
	v_lshlrev_b32_e32 v8, 15, v5
	v_and_b32_e32 v8, 0xffff0000, v8
	v_lshl_add_u32 v6, v6, 12, v8
	v_and_b32_e32 v5, 1, v5
	v_lshl_or_b32 v5, v5, 6, v6
	v_lshl_add_u32 v132, v7, 1, v5
	v_lshlrev_b32_e32 v5, 15, v2
	v_and_b32_e32 v5, 0xffff0000, v5
	s_waitcnt vmcnt(6)
	v_lshl_add_u32 v3, v3, 12, v5
	v_and_b32_e32 v2, 1, v2
	v_readlane_b32 s15, v248, 31
	v_lshl_or_b32 v2, v2, 6, v3
	s_mov_b32 s39, s14
	v_readlane_b32 s14, v248, 16
	v_mov_b32_e32 v133, v1
	v_lshl_add_u32 v134, v4, 1, v2
	v_mov_b32_e32 v135, v1
	s_mov_b32 s38, 0
	v_add_u32_e32 v157, 0, v19
	s_mov_b32 s40, s14
	s_mov_b64 s[20:21], s[24:25]
	s_mov_b64 s[22:23], s[26:27]
	s_barrier
	v_readlane_b32 s15, v248, 17

; #define G_STA(bufoff, gbase, ld) G_STAGE(bufoff, gbase, RA0, RA1, ld)
; #define G_STB(bufoff, gbase, ld) G_STAGE(bufoff, gbase, RB0, RB1, ld)
; #define G_LDA(dst, b, h) do { _Pragma("unroll") for (int m = 0; m < 4; ++m) _Pragma("unroll") for (int k = 0; k < 2; ++k) dst[m][k] = *(const LAS bf16x8*)(lds + G_SA(b, h) + aoff + m * 2048 + k * 1024); } while (0)
; #define G_LDB(dst, b, h) do { _Pragma("unroll") for (int n = 0; n < 2; ++n) _Pragma("unroll") for (int k = 0; k < 2; ++k) dst[n][k] = *(const LAS bf16x8*)(lds + G_SB(b, h) + boff + n * 2048 + k * 1024); } while (0)
; #define G_MMA(ai, bj, At, Bt) do { __builtin_amdgcn_s_setprio(1); _Pragma("unroll") for (int m = 0; m < 4; ++m) _Pragma("unroll") for (int n = 0; n < 2; ++n) _Pragma("unroll") for (int k = 0; k < 2; ++k) \
;         acc[ai][bj][m][n] = __builtin_amdgcn_mfma_f32_16x16x32_bf16(Bt[n][k], At[m][k], acc[ai][bj][m][n], 0, 0, 0); __builtin_amdgcn_s_setprio(0); } while (0)
; #define G_WAIT_L(n) asm volatile("s_waitcnt lgkmcnt(" #n ")" ::: "memory")
; #define G_BAR __builtin_amdgcn_s_barrier()
; #define G_SCHED __builtin_amdgcn_sched_barrier(0)
; template <bool PERM, class SchedT, class Epi>
; __device__ __forceinline__ void gemm_phase(LAS unsigned char* lds, const SchedT& S, const Epi& E) {
;     ...
;         for (int t = 0; t < nt; t += 2) {
;             const bool last = (t == nt - 2);
;             const char* a1 = cA + (size_t)(t + 1) * kstep;
;             const char* a2 = last ? nA : cA + (size_t)(t + 2) * kstep; const char* b2 = last ? nB : cB + (size_t)(t + 2) * kstep;
;             const char* a3 = a2 + kstep; const char* b3 = b2 + kstep;
;             const int wlda = last ? nlda : lda, wK = last ? nK : K;
;             G_LDB(B0, 0, 0); G_SCHED; G_LDA(At, 0, 0); G_STA(G_SA(1, 1), a1 + HSTEP(lda), lda);
;             G_WAIT_L(8); G_BAR; G_WAIT_L(0); G_MMA(0, 0, At, B0); G_BAR; G_SCHED;
;             G_LDB(B1, 0, 1); G_STB(G_SB(0, 0), b2, wK);
;             G_BAR; G_WAIT_L(0); G_MMA(0, 1, At, B1); G_BAR;
;             G_LDA(At, 0, 1); G_STA(G_SA(0, 0), a2, wlda);
;             G_BAR; G_WAIT_L(0); G_MMA(1, 0, At, B0); G_BAR; G_SCHED;
.LBB0_366:
	s_add_u32 s26, s24, 0xfff80080
	s_addc_u32 s27, s25, -1
	s_add_i32 s42, 0, 0x10000
	v_add_u32_e32 v148, s42, v155
	ds_read_b128 v[136:139], v148
	ds_read_b128 v[140:143], v148 offset:1024
	ds_read_b128 v[144:147], v148 offset:2048
	ds_read_b128 v[148:151], v148 offset:3072
	s_cmp_eq_u32 s41, 28
	s_cselect_b32 s29, s21, s27
	s_cselect_b32 s28, s20, s26
	s_cselect_b32 s27, s23, s19
	s_cselect_b32 s26, s22, s17
	v_lshl_add_u64 v[152:153], s[24:25], 0, v[132:133]
	s_add_i32 m0, s30, 0xc000
	ds_read_b128 v[160:163], v157
	ds_read_b128 v[164:167], v157 offset:1024
	ds_read_b128 v[168:171], v157 offset:2048
	ds_read_b128 v[172:175], v157 offset:3072
	ds_read_b128 v[176:179], v157 offset:4096
	ds_read_b128 v[192:195], v157 offset:5120
	ds_read_b128 v[196:199], v157 offset:6144
	ds_read_b128 v[200:203], v157 offset:7168
	global_load_lds_dwordx4 v[152:153], off
	v_lshl_add_u64 v[152:153], s[24:25], 0, v[134:135]
	s_add_i32 m0, s30, 0xe000
	s_nop 0
	global_load_lds_dwordx4 v[152:153], off
	s_waitcnt lgkmcnt(8)
	s_barrier
	s_waitcnt lgkmcnt(0)
	s_setprio 1
	s_waitcnt lgkmcnt(0)
	v_mfma_f32_16x16x32_bf16 v[66:69], v[136:139], v[160:163], v[66:69]
	v_mfma_f32_16x16x32_bf16 v[70:73], v[144:147], v[160:163], v[70:73]
	v_mfma_f32_16x16x32_bf16 v[82:85], v[136:139], v[168:171], v[82:85]
	v_mfma_f32_16x16x32_bf16 v[110:113], v[144:147], v[168:171], v[110:113]
	v_mfma_f32_16x16x32_bf16 v[126:129], v[136:139], v[176:179], v[126:129]
	v_mfma_f32_16x16x32_bf16 v[118:121], v[144:147], v[176:179], v[118:121]
	v_mfma_f32_16x16x32_bf16 v[122:125], v[136:139], v[196:199], v[122:125]
	v_mfma_f32_16x16x32_bf16 v[114:117], v[144:147], v[196:199], v[114:117]
	v_mfma_f32_16x16x32_bf16 v[66:69], v[140:143], v[164:167], v[66:69]
	v_mfma_f32_16x16x32_bf16 v[70:73], v[148:151], v[164:167], v[70:73]
	v_mfma_f32_16x16x32_bf16 v[82:85], v[140:143], v[172:175], v[82:85]
	v_mfma_f32_16x16x32_bf16 v[110:113], v[148:151], v[172:175], v[110:113]
	v_mfma_f32_16x16x32_bf16 v[126:129], v[140:143], v[192:195], v[126:129]
	v_mfma_f32_16x16x32_bf16 v[118:121], v[148:151], v[192:195], v[118:121]
	v_mfma_f32_16x16x32_bf16 v[122:125], v[140:143], v[200:203], v[122:125]
	v_mfma_f32_16x16x32_bf16 v[114:117], v[148:151], v[200:203], v[114:117]
	s_setprio 0
	s_barrier
	s_add_i32 s44, 0, 0x14000
	v_add_u32_e32 v152, s44, v155
	s_add_i32 s42, s42, s5
	ds_read_b128 v[204:207], v152
	ds_read_b128 v[208:211], v152 offset:1024
	ds_read_b128 v[212:215], v152 offset:2048
	ds_read_b128 v[216:219], v152 offset:3072
	v_lshl_add_u64 v[152:153], s[26:27], 0, v[0:1]
	s_mov_b32 m0, s42
	v_lshl_add_u64 v[220:221], s[26:27], 0, v[130:131]
	global_load_lds_dwordx4 v[152:153], off
	s_add_i32 m0, s42, 0x2000
	s_nop 0
	global_load_lds_dwordx4 v[220:221], off
	s_barrier
	s_waitcnt lgkmcnt(0)
	s_setprio 1
	s_waitcnt lgkmcnt(0)
	v_mfma_f32_16x16x32_bf16 v[74:77], v[204:207], v[160:163], v[74:77]
	v_mfma_f32_16x16x32_bf16 v[78:81], v[212:215], v[160:163], v[78:81]
	v_mfma_f32_16x16x32_bf16 v[98:101], v[204:207], v[168:171], v[98:101]
	v_mfma_f32_16x16x32_bf16 v[86:89], v[212:215], v[168:171], v[86:89]
	v_mfma_f32_16x16x32_bf16 v[106:109], v[204:207], v[176:179], v[106:109]
	v_mfma_f32_16x16x32_bf16 v[94:97], v[212:215], v[176:179], v[94:97]
	v_mfma_f32_16x16x32_bf16 v[102:105], v[204:207], v[196:199], v[102:105]
	v_mfma_f32_16x16x32_bf16 v[90:93], v[212:215], v[196:199], v[90:93]
	v_mfma_f32_16x16x32_bf16 v[74:77], v[208:211], v[164:167], v[74:77]
	v_mfma_f32_16x16x32_bf16 v[78:81], v[216:219], v[164:167], v[78:81]
	v_mfma_f32_16x16x32_bf16 v[98:101], v[208:211], v[172:175], v[98:101]
	v_mfma_f32_16x16x32_bf16 v[86:89], v[216:219], v[172:175], v[86:89]
	v_mfma_f32_16x16x32_bf16 v[106:109], v[208:211], v[192:195], v[106:109]
	v_mfma_f32_16x16x32_bf16 v[94:97], v[216:219], v[192:195], v[94:97]
	v_mfma_f32_16x16x32_bf16 v[102:105], v[208:211], v[200:203], v[102:105]
	v_mfma_f32_16x16x32_bf16 v[90:93], v[216:219], v[200:203], v[90:93]
	s_setprio 0
	s_mov_b32 m0, s30
	v_lshl_add_u64 v[222:223], s[28:29], 0, v[0:1]
	s_barrier
	ds_read_b128 v[160:163], v157 offset:16384
	ds_read_b128 v[164:167], v157 offset:17408
	ds_read_b128 v[168:171], v157 offset:18432
	ds_read_b128 v[172:175], v157 offset:19456
	ds_read_b128 v[176:179], v157 offset:20480
	ds_read_b128 v[192:195], v157 offset:21504
	ds_read_b128 v[196:199], v157 offset:22528
	ds_read_b128 v[200:203], v157 offset:23552
	global_load_lds_dwordx4 v[222:223], off
	v_lshl_add_u64 v[224:225], s[28:29], 0, v[130:131]
	s_mov_b32 m0, s31
	s_nop 0
	global_load_lds_dwordx4 v[224:225], off
	s_barrier
	s_waitcnt lgkmcnt(0)
	s_setprio 1
	s_waitcnt lgkmcnt(0)
	v_mfma_f32_16x16x32_bf16 v[62:65], v[136:139], v[160:163], v[62:65]
	v_mfma_f32_16x16x32_bf16 v[58:61], v[144:147], v[160:163], v[58:61]
	v_mfma_f32_16x16x32_bf16 v[46:49], v[136:139], v[168:171], v[46:49]
	v_mfma_f32_16x16x32_bf16 v[42:45], v[144:147], v[168:171], v[42:45]
	v_mfma_f32_16x16x32_bf16 v[30:33], v[136:139], v[176:179], v[30:33]
	v_mfma_f32_16x16x32_bf16 v[26:29], v[144:147], v[176:179], v[26:29]
	v_mfma_f32_16x16x32_bf16 v[14:17], v[136:139], v[196:199], v[14:17]
	v_mfma_f32_16x16x32_bf16 v[10:13], v[144:147], v[196:199], v[10:13]
	v_mfma_f32_16x16x32_bf16 v[62:65], v[140:143], v[164:167], v[62:65]
	v_mfma_f32_16x16x32_bf16 v[58:61], v[148:151], v[164:167], v[58:61]
	v_mfma_f32_16x16x32_bf16 v[46:49], v[140:143], v[172:175], v[46:49]
	v_mfma_f32_16x16x32_bf16 v[42:45], v[148:151], v[172:175], v[42:45]
	v_mfma_f32_16x16x32_bf16 v[30:33], v[140:143], v[192:195], v[30:33]
	v_mfma_f32_16x16x32_bf16 v[26:29], v[148:151], v[192:195], v[26:29]
	v_mfma_f32_16x16x32_bf16 v[14:17], v[140:143], v[200:203], v[14:17]
	v_mfma_f32_16x16x32_bf16 v[10:13], v[148:151], v[200:203], v[10:13]
	s_setprio 0
	s_barrier
; #define G_STA(bufoff, gbase, ld) G_STAGE(bufoff, gbase, RA0, RA1, ld)
; #define G_STB(bufoff, gbase, ld) G_STAGE(bufoff, gbase, RB0, RB1, ld)
; #define G_LDA(dst, b, h) do { _Pragma("unroll") for (int m = 0; m < 4; ++m) _Pragma("unroll") for (int k = 0; k < 2; ++k) dst[m][k] = *(const LAS bf16x8*)(lds + G_SA(b, h) + aoff + m * 2048 + k * 1024); } while (0)
; #define G_LDB(dst, b, h) do { _Pragma("unroll") for (int n = 0; n < 2; ++n) _Pragma("unroll") for (int k = 0; k < 2; ++k) dst[n][k] = *(const LAS bf16x8*)(lds + G_SB(b, h) + boff + n * 2048 + k * 1024); } while (0)
; #define G_MMA(ai, bj, At, Bt) do { __builtin_amdgcn_s_setprio(1); _Pragma("unroll") for (int m = 0; m < 4; ++m) _Pragma("unroll") for (int n = 0; n < 2; ++n) _Pragma("unroll") for (int k = 0; k < 2; ++k) \
;         acc[ai][bj][m][n] = __builtin_amdgcn_mfma_f32_16x16x32_bf16(Bt[n][k], At[m][k], acc[ai][bj][m][n], 0, 0, 0); __builtin_amdgcn_s_setprio(0); } while (0)
; #define G_WAIT_V(n) asm volatile("s_waitcnt vmcnt(" #n ")" ::: "memory")
; #define G_WAIT_L(n) asm volatile("s_waitcnt lgkmcnt(" #n ")" ::: "memory")
; #define G_BAR __builtin_amdgcn_s_barrier()
; #define G_SCHED __builtin_amdgcn_sched_barrier(0)
; template <bool PERM, class SchedT, class Epi>
; __device__ __forceinline__ void gemm_phase(LAS unsigned char* lds, const SchedT& S, const Epi& E) {
;     ...
;             G_STB(G_SB(0, 1), b2 + HSTEP(wK), wK);
;             G_WAIT_V(6); G_BAR; G_MMA(1, 1, At, B1); G_BAR;
;             G_LDB(B0, 1, 0); G_SCHED; G_LDA(At, 1, 0); G_STA(G_SA(0, 1), a2 + HSTEP(wlda), wlda);
;             G_WAIT_L(8); G_BAR; G_WAIT_L(0); G_MMA(0, 0, At, B0); G_BAR; G_SCHED;
;             G_LDB(B1, 1, 1); G_STB(G_SB(1, 0), b3, wK);
;             G_BAR; G_WAIT_L(0); G_MMA(0, 1, At, B1); G_BAR;
;             G_LDA(At, 1, 1); G_STA(G_SA(1, 0), a3, wlda);
;             G_BAR; G_WAIT_L(0); G_MMA(1, 0, At, B0); G_BAR; G_SCHED;
	s_add_u32 s42, s26, 0x80000
	s_addc_u32 s43, s27, 0
	s_add_i32 s44, s44, s5
	v_lshl_add_u64 v[136:137], s[42:43], 0, v[0:1]
	s_mov_b32 m0, s44
	s_nop 0
	global_load_lds_dwordx4 v[136:137], off
	v_lshl_add_u64 v[136:137], s[42:43], 0, v[130:131]
	s_add_i32 m0, s44, 0x2000
	s_nop 0
	global_load_lds_dwordx4 v[136:137], off
	s_waitcnt vmcnt(6)
	s_barrier
	s_setprio 1
	v_mfma_f32_16x16x32_bf16 v[54:57], v[204:207], v[160:163], v[54:57]
	v_mfma_f32_16x16x32_bf16 v[50:53], v[212:215], v[160:163], v[50:53]
	v_mfma_f32_16x16x32_bf16 v[38:41], v[204:207], v[168:171], v[38:41]
	v_mfma_f32_16x16x32_bf16 v[34:37], v[212:215], v[168:171], v[34:37]
	v_mfma_f32_16x16x32_bf16 v[22:25], v[204:207], v[176:179], v[22:25]
	v_mfma_f32_16x16x32_bf16 v[18:21], v[212:215], v[176:179], v[18:21]
	v_mfma_f32_16x16x32_bf16 v[6:9], v[204:207], v[196:199], v[6:9]
	v_mfma_f32_16x16x32_bf16 v[2:5], v[212:215], v[196:199], v[2:5]
	v_mfma_f32_16x16x32_bf16 v[54:57], v[208:211], v[164:167], v[54:57]
	v_mfma_f32_16x16x32_bf16 v[50:53], v[216:219], v[164:167], v[50:53]
	v_mfma_f32_16x16x32_bf16 v[38:41], v[208:211], v[172:175], v[38:41]
	v_mfma_f32_16x16x32_bf16 v[34:37], v[216:219], v[172:175], v[34:37]
	v_mfma_f32_16x16x32_bf16 v[22:25], v[208:211], v[192:195], v[22:25]
	v_mfma_f32_16x16x32_bf16 v[18:21], v[216:219], v[192:195], v[18:21]
	v_mfma_f32_16x16x32_bf16 v[6:9], v[208:211], v[200:203], v[6:9]
	v_mfma_f32_16x16x32_bf16 v[2:5], v[216:219], v[200:203], v[2:5]
	s_setprio 0
	s_add_i32 s42, 0, 0x18000
	v_add_u32_e32 v148, s42, v155
	s_barrier
	ds_read_b128 v[136:139], v148
	ds_read_b128 v[140:143], v148 offset:1024
	ds_read_b128 v[144:147], v148 offset:2048
	ds_read_b128 v[148:151], v148 offset:3072
	s_add_u32 s28, s28, 0x80000
	s_addc_u32 s29, s29, 0
	s_mov_b32 m0, s34
	v_lshl_add_u64 v[204:205], s[28:29], 0, v[0:1]
	ds_read_b128 v[160:163], v157 offset:32768
	ds_read_b128 v[164:167], v157 offset:33792
	ds_read_b128 v[168:171], v157 offset:34816
	ds_read_b128 v[172:175], v157 offset:35840
	ds_read_b128 v[176:179], v157 offset:36864
	ds_read_b128 v[192:195], v157 offset:37888
	ds_read_b128 v[196:199], v157 offset:38912
	ds_read_b128 v[200:203], v157 offset:39936
	global_load_lds_dwordx4 v[204:205], off
	v_lshl_add_u64 v[204:205], s[28:29], 0, v[130:131]
	s_mov_b32 m0, s35
	s_nop 0
	global_load_lds_dwordx4 v[204:205], off
	s_waitcnt lgkmcnt(8)
	s_barrier
	s_waitcnt lgkmcnt(0)
	s_setprio 1
	s_waitcnt lgkmcnt(0)
	v_mfma_f32_16x16x32_bf16 v[66:69], v[136:139], v[160:163], v[66:69]
	v_mfma_f32_16x16x32_bf16 v[70:73], v[144:147], v[160:163], v[70:73]
	v_mfma_f32_16x16x32_bf16 v[82:85], v[136:139], v[168:171], v[82:85]
	v_mfma_f32_16x16x32_bf16 v[110:113], v[144:147], v[168:171], v[110:113]
	v_mfma_f32_16x16x32_bf16 v[126:129], v[136:139], v[176:179], v[126:129]
	v_mfma_f32_16x16x32_bf16 v[118:121], v[144:147], v[176:179], v[118:121]
	v_mfma_f32_16x16x32_bf16 v[122:125], v[136:139], v[196:199], v[122:125]
	v_mfma_f32_16x16x32_bf16 v[114:117], v[144:147], v[196:199], v[114:117]
	v_mfma_f32_16x16x32_bf16 v[66:69], v[140:143], v[164:167], v[66:69]
	v_mfma_f32_16x16x32_bf16 v[70:73], v[148:151], v[164:167], v[70:73]
	v_mfma_f32_16x16x32_bf16 v[82:85], v[140:143], v[172:175], v[82:85]
	v_mfma_f32_16x16x32_bf16 v[110:113], v[148:151], v[172:175], v[110:113]
	v_mfma_f32_16x16x32_bf16 v[126:129], v[140:143], v[192:195], v[126:129]
	v_mfma_f32_16x16x32_bf16 v[118:121], v[148:151], v[192:195], v[118:121]
	v_mfma_f32_16x16x32_bf16 v[122:125], v[140:143], v[200:203], v[122:125]
	v_mfma_f32_16x16x32_bf16 v[114:117], v[148:151], v[200:203], v[114:117]
	s_setprio 0
	s_barrier
	s_add_i32 s28, 0, 0x1c000
	s_add_i32 s29, s42, s5
	v_add_u32_e32 v216, s28, v155
	v_lshl_add_u64 v[152:153], v[152:153], 0, s[78:79]
	s_mov_b32 m0, s29
	ds_read_b128 v[204:207], v216
	ds_read_b128 v[208:211], v216 offset:1024
	ds_read_b128 v[212:215], v216 offset:2048
	ds_read_b128 v[216:219], v216 offset:3072
	global_load_lds_dwordx4 v[152:153], off
	v_lshl_add_u64 v[152:153], v[220:221], 0, s[78:79]
	s_add_i32 m0, s29, 0x2000
	s_nop 0
	global_load_lds_dwordx4 v[152:153], off
	s_barrier
	s_waitcnt lgkmcnt(0)
	s_setprio 1
	s_waitcnt lgkmcnt(0)
	v_mfma_f32_16x16x32_bf16 v[74:77], v[204:207], v[160:163], v[74:77]
	v_mfma_f32_16x16x32_bf16 v[78:81], v[212:215], v[160:163], v[78:81]
	v_mfma_f32_16x16x32_bf16 v[98:101], v[204:207], v[168:171], v[98:101]
	v_mfma_f32_16x16x32_bf16 v[86:89], v[212:215], v[168:171], v[86:89]
	v_mfma_f32_16x16x32_bf16 v[106:109], v[204:207], v[176:179], v[106:109]
	v_mfma_f32_16x16x32_bf16 v[94:97], v[212:215], v[176:179], v[94:97]
	v_mfma_f32_16x16x32_bf16 v[102:105], v[204:207], v[196:199], v[102:105]
	v_mfma_f32_16x16x32_bf16 v[90:93], v[212:215], v[196:199], v[90:93]
	v_mfma_f32_16x16x32_bf16 v[74:77], v[208:211], v[164:167], v[74:77]
	v_mfma_f32_16x16x32_bf16 v[78:81], v[216:219], v[164:167], v[78:81]
	v_mfma_f32_16x16x32_bf16 v[98:101], v[208:211], v[172:175], v[98:101]
	v_mfma_f32_16x16x32_bf16 v[86:89], v[216:219], v[172:175], v[86:89]
	v_mfma_f32_16x16x32_bf16 v[106:109], v[208:211], v[192:195], v[106:109]
	v_mfma_f32_16x16x32_bf16 v[94:97], v[216:219], v[192:195], v[94:97]
	v_mfma_f32_16x16x32_bf16 v[102:105], v[208:211], v[200:203], v[102:105]
	v_mfma_f32_16x16x32_bf16 v[90:93], v[216:219], v[200:203], v[90:93]
	s_setprio 0
	s_mov_b32 m0, s36
	v_lshl_add_u64 v[152:153], v[222:223], 0, s[78:79]
	s_barrier
	ds_read_b128 v[160:163], v157 offset:49152
	ds_read_b128 v[164:167], v157 offset:50176
	ds_read_b128 v[168:171], v157 offset:51200
	ds_read_b128 v[172:175], v157 offset:52224
	ds_read_b128 v[176:179], v157 offset:53248
	ds_read_b128 v[192:195], v157 offset:54272
	ds_read_b128 v[196:199], v157 offset:55296
	ds_read_b128 v[200:203], v157 offset:56320
	global_load_lds_dwordx4 v[152:153], off
	v_lshl_add_u64 v[152:153], v[224:225], 0, s[78:79]
	s_mov_b32 m0, s37
	s_nop 0
	global_load_lds_dwordx4 v[152:153], off
	s_barrier
;     __device__ __forceinline__ void operator()(f32x4 (&acc)[2][2][4][2], const UnitD& u, int wr, int wc, int fr, int fq) const {
;         const int row0 = u.pm * BM + wr * 64 + fr, col0 = u.pn * BM + wc * 32 + 4 * fq;
; #pragma unroll
;         for (int ai = 0; ai < 2; ++ai)
; #pragma unroll
;             for (int m = 0; m < 4; ++m) { const int row = row0 + ai * HALF + m * 16;
;                 const float* xr = (row < TP ? xp + (size_t)row * 2048 : xs + (size_t)(row - TP) * 2048) + col0;
; #pragma unroll
;                 for (int bj = 0; bj < 2; ++bj)
; #pragma unroll
;                     for (int n = 0; n < 2; ++n) acc[ai][bj][m][n] += *(const f32x4*)(xr + bj * HALF + n * 16);
;                 if (m & 1) asm volatile("" ::: "memory"); }
; #pragma unroll
;         for (int ai = 0; ai < 2; ++ai)
; #pragma unroll
;             for (int m = 0; m < 4; ++m) { const int row = row0 + ai * HALF + m * 16; float* orow = out + (size_t)row * 2048 + col0;
; #pragma unroll
;                 for (int bj = 0; bj < 2; ++bj)
; #pragma unroll
;                     for (int n = 0; n < 2; ++n) *(f32x4*)(orow + bj * HALF + n * 16) = acc[ai][bj][m][n]; }
	s_waitcnt lgkmcnt(0)
	s_setprio 1
	s_waitcnt lgkmcnt(0)
	v_mfma_f32_16x16x32_bf16 v[62:65], v[136:139], v[160:163], v[62:65]
	v_mfma_f32_16x16x32_bf16 v[58:61], v[144:147], v[160:163], v[58:61]
	v_mfma_f32_16x16x32_bf16 v[46:49], v[136:139], v[168:171], v[46:49]
	v_mfma_f32_16x16x32_bf16 v[42:45], v[144:147], v[168:171], v[42:45]
	v_mfma_f32_16x16x32_bf16 v[30:33], v[136:139], v[176:179], v[30:33]
	v_mfma_f32_16x16x32_bf16 v[26:29], v[144:147], v[176:179], v[26:29]
	v_mfma_f32_16x16x32_bf16 v[14:17], v[136:139], v[196:199], v[14:17]
	v_mfma_f32_16x16x32_bf16 v[10:13], v[144:147], v[196:199], v[10:13]
	v_mfma_f32_16x16x32_bf16 v[62:65], v[140:143], v[164:167], v[62:65]
	v_mfma_f32_16x16x32_bf16 v[58:61], v[148:151], v[164:167], v[58:61]
	v_mfma_f32_16x16x32_bf16 v[46:49], v[140:143], v[172:175], v[46:49]
	v_mfma_f32_16x16x32_bf16 v[42:45], v[148:151], v[172:175], v[42:45]
	v_mfma_f32_16x16x32_bf16 v[30:33], v[140:143], v[192:195], v[30:33]
	v_mfma_f32_16x16x32_bf16 v[26:29], v[148:151], v[192:195], v[26:29]
	v_mfma_f32_16x16x32_bf16 v[14:17], v[140:143], v[200:203], v[14:17]
	v_mfma_f32_16x16x32_bf16 v[10:13], v[148:151], v[200:203], v[10:13]
	s_setprio 0
	s_barrier
	s_add_u32 s26, s26, 0x80080
	s_addc_u32 s27, s27, 0
	s_add_i32 s28, s28, s5
	v_lshl_add_u64 v[136:137], s[26:27], 0, v[0:1]
	s_mov_b32 m0, s28
	s_nop 0
	global_load_lds_dwordx4 v[136:137], off
	v_lshl_add_u64 v[136:137], s[26:27], 0, v[130:131]
	s_add_i32 m0, s28, 0x2000
	s_nop 0
	global_load_lds_dwordx4 v[136:137], off
	s_waitcnt vmcnt(6)
	s_barrier
	s_setprio 1
	v_mfma_f32_16x16x32_bf16 v[54:57], v[204:207], v[160:163], v[54:57]
	v_mfma_f32_16x16x32_bf16 v[50:53], v[212:215], v[160:163], v[50:53]
	v_mfma_f32_16x16x32_bf16 v[38:41], v[204:207], v[168:171], v[38:41]
	v_mfma_f32_16x16x32_bf16 v[34:37], v[212:215], v[168:171], v[34:37]
	v_mfma_f32_16x16x32_bf16 v[22:25], v[204:207], v[176:179], v[22:25]
	v_mfma_f32_16x16x32_bf16 v[18:21], v[212:215], v[176:179], v[18:21]
	v_mfma_f32_16x16x32_bf16 v[6:9], v[204:207], v[196:199], v[6:9]
	v_mfma_f32_16x16x32_bf16 v[2:5], v[212:215], v[196:199], v[2:5]
	v_mfma_f32_16x16x32_bf16 v[54:57], v[208:211], v[164:167], v[54:57]
	v_mfma_f32_16x16x32_bf16 v[50:53], v[216:219], v[164:167], v[50:53]
	v_mfma_f32_16x16x32_bf16 v[38:41], v[208:211], v[172:175], v[38:41]
	v_mfma_f32_16x16x32_bf16 v[34:37], v[216:219], v[172:175], v[34:37]
	v_mfma_f32_16x16x32_bf16 v[22:25], v[208:211], v[192:195], v[22:25]
	v_mfma_f32_16x16x32_bf16 v[18:21], v[216:219], v[192:195], v[18:21]
	v_mfma_f32_16x16x32_bf16 v[6:9], v[208:211], v[200:203], v[6:9]
	v_mfma_f32_16x16x32_bf16 v[2:5], v[216:219], v[200:203], v[2:5]
	s_setprio 0
	s_add_i32 s41, s41, 2
	s_add_u32 s24, s24, 0x100
	s_addc_u32 s25, s25, 0
	s_add_u32 s17, s17, 0x100
	s_addc_u32 s19, s19, 0
	s_cmp_gt_u32 s41, 29
	s_barrier
	s_cbranch_scc0 .LBB0_366
	v_lshl_add_u32 v208, s39, 8, v154
	v_lshl_or_b32 v209, s40, 8, v156
	v_lshlrev_b32_e32 v209, 2, v209
	v_lshl_add_u32 v208, v208, 13, v209
	v_mov_b32_e32 v209, 0
	v_lshl_add_u64 v[210:211], s[8:9], 0, v[208:209]
	v_lshl_add_u64 v[212:213], s[12:13], 0, v[208:209]
	v_mov_b32_e32 v214, v210
	v_mov_b32_e32 v215, v211
	global_load_dwordx4 v[136:139], v[214:215], off
	global_load_dwordx4 v[140:143], v[214:215], off offset:64
	global_load_dwordx4 v[144:147], v[214:215], off offset:512
	global_load_dwordx4 v[148:151], v[214:215], off offset:576
	v_add_co_u32_e32 v214, vcc, 0x20000, v210
	s_nop 1
	v_addc_co_u32_e32 v215, vcc, 0, v211, vcc
	global_load_dwordx4 v[160:163], v[214:215], off
	global_load_dwordx4 v[164:167], v[214:215], off offset:64
	global_load_dwordx4 v[168:171], v[214:215], off offset:512
	global_load_dwordx4 v[172:175], v[214:215], off offset:576
	v_add_co_u32_e32 v214, vcc, 0x40000, v210
	s_nop 1
	v_addc_co_u32_e32 v215, vcc, 0, v211, vcc
	global_load_dwordx4 v[192:195], v[214:215], off
	global_load_dwordx4 v[196:199], v[214:215], off offset:64
	global_load_dwordx4 v[200:203], v[214:215], off offset:512
	global_load_dwordx4 v[204:207], v[214:215], off offset:576
	ds_write_b128 v251, v[66:69]
	ds_read_b128 v[66:69], v252
	ds_write_b128 v251, v[70:73]
	ds_read_b128 v[70:73], v252
	ds_write_b128 v251, v[74:77]
	ds_read_b128 v[74:77], v252
	ds_write_b128 v251, v[78:81]
	ds_read_b128 v[78:81], v252
	v_mov_b32_e32 v216, v212
	v_mov_b32_e32 v217, v213
	s_waitcnt vmcnt(8)
	s_waitcnt lgkmcnt(6)
	v_pk_add_f32 v[66:67], v[66:67], v[136:137]
	v_pk_add_f32 v[68:69], v[68:69], v[138:139]
	s_waitcnt lgkmcnt(4)
	v_pk_add_f32 v[70:71], v[70:71], v[140:141]
	v_pk_add_f32 v[72:73], v[72:73], v[142:143]
	s_waitcnt lgkmcnt(2)
	v_pk_add_f32 v[74:75], v[74:75], v[144:145]
	v_pk_add_f32 v[76:77], v[76:77], v[146:147]
	s_waitcnt lgkmcnt(0)
	v_pk_add_f32 v[78:79], v[78:79], v[148:149]
	v_pk_add_f32 v[80:81], v[80:81], v[150:151]
	global_store_dwordx4 v[216:217], v[66:69], off
	global_store_dwordx4 v[216:217], v[70:73], off offset:64
	global_store_dwordx4 v[216:217], v[74:77], off offset:512
	global_store_dwordx4 v[216:217], v[78:81], off offset:576
	v_add_co_u32_e32 v214, vcc, 0x60000, v210
	s_nop 1
	v_addc_co_u32_e32 v215, vcc, 0, v211, vcc
	global_load_dwordx4 v[136:139], v[214:215], off
	global_load_dwordx4 v[140:143], v[214:215], off offset:64
	global_load_dwordx4 v[144:147], v[214:215], off offset:512
	global_load_dwordx4 v[148:151], v[214:215], off offset:576
	ds_write_b128 v251, v[82:85]
	ds_read_b128 v[82:85], v252
	ds_write_b128 v251, v[110:113]
	ds_read_b128 v[110:113], v252
	ds_write_b128 v251, v[98:101]
	ds_read_b128 v[98:101], v252
	ds_write_b128 v251, v[86:89]
	ds_read_b128 v[86:89], v252
	v_add_co_u32_e32 v216, vcc, 0x20000, v212
	s_nop 1
	v_addc_co_u32_e32 v217, vcc, 0, v213, vcc
	s_waitcnt vmcnt(12)
;     __device__ __forceinline__ void operator()(f32x4 (&acc)[2][2][4][2], const UnitD& u, int wr, int wc, int fr, int fq) const {
;         const int row0 = u.pm * BM + wr * 64 + fr, col0 = u.pn * BM + wc * 32 + 4 * fq;
; #pragma unroll
;         for (int ai = 0; ai < 2; ++ai)
; #pragma unroll
;             for (int m = 0; m < 4; ++m) { const int row = row0 + ai * HALF + m * 16;
;                 const float* xr = (row < TP ? xp + (size_t)row * 2048 : xs + (size_t)(row - TP) * 2048) + col0;
; #pragma unroll
;                 for (int bj = 0; bj < 2; ++bj)
; #pragma unroll
;                     for (int n = 0; n < 2; ++n) acc[ai][bj][m][n] += *(const f32x4*)(xr + bj * HALF + n * 16);
;                 if (m & 1) asm volatile("" ::: "memory"); }
; #pragma unroll
;         for (int ai = 0; ai < 2; ++ai)
; #pragma unroll
;             for (int m = 0; m < 4; ++m) { const int row = row0 + ai * HALF + m * 16; float* orow = out + (size_t)row * 2048 + col0;
; #pragma unroll
;                 for (int bj = 0; bj < 2; ++bj)
; #pragma unroll
;                     for (int n = 0; n < 2; ++n) *(f32x4*)(orow + bj * HALF + n * 16) = acc[ai][bj][m][n]; }
	s_waitcnt lgkmcnt(6)
	v_pk_add_f32 v[82:83], v[82:83], v[160:161]
	v_pk_add_f32 v[84:85], v[84:85], v[162:163]
	s_waitcnt lgkmcnt(4)
	v_pk_add_f32 v[110:111], v[110:111], v[164:165]
	v_pk_add_f32 v[112:113], v[112:113], v[166:167]
	s_waitcnt lgkmcnt(2)
	v_pk_add_f32 v[98:99], v[98:99], v[168:169]
	v_pk_add_f32 v[100:101], v[100:101], v[170:171]
	s_waitcnt lgkmcnt(0)
	v_pk_add_f32 v[86:87], v[86:87], v[172:173]
	v_pk_add_f32 v[88:89], v[88:89], v[174:175]
	global_store_dwordx4 v[216:217], v[82:85], off
	global_store_dwordx4 v[216:217], v[110:113], off offset:64
	global_store_dwordx4 v[216:217], v[98:101], off offset:512
	global_store_dwordx4 v[216:217], v[86:89], off offset:576
	v_add_co_u32_e32 v214, vcc, 0x100000, v210
	s_nop 1
	v_addc_co_u32_e32 v215, vcc, 0, v211, vcc
	global_load_dwordx4 v[160:163], v[214:215], off
	global_load_dwordx4 v[164:167], v[214:215], off offset:64
	global_load_dwordx4 v[168:171], v[214:215], off offset:512
	global_load_dwordx4 v[172:175], v[214:215], off offset:576
	ds_write_b128 v251, v[126:129]
	ds_read_b128 v[126:129], v252
	ds_write_b128 v251, v[118:121]
	ds_read_b128 v[118:121], v252
	ds_write_b128 v251, v[106:109]
	ds_read_b128 v[106:109], v252
	ds_write_b128 v251, v[94:97]
	ds_read_b128 v[94:97], v252
	v_add_co_u32_e32 v216, vcc, 0x40000, v212
	s_nop 1
	v_addc_co_u32_e32 v217, vcc, 0, v213, vcc
	s_waitcnt vmcnt(16)
	s_waitcnt lgkmcnt(6)
	v_pk_add_f32 v[126:127], v[126:127], v[192:193]
	v_pk_add_f32 v[128:129], v[128:129], v[194:195]
	s_waitcnt lgkmcnt(4)
	v_pk_add_f32 v[118:119], v[118:119], v[196:197]
	v_pk_add_f32 v[120:121], v[120:121], v[198:199]
	s_waitcnt lgkmcnt(2)
	v_pk_add_f32 v[106:107], v[106:107], v[200:201]
	v_pk_add_f32 v[108:109], v[108:109], v[202:203]
	s_waitcnt lgkmcnt(0)
	v_pk_add_f32 v[94:95], v[94:95], v[204:205]
	v_pk_add_f32 v[96:97], v[96:97], v[206:207]
	global_store_dwordx4 v[216:217], v[126:129], off
	global_store_dwordx4 v[216:217], v[118:121], off offset:64
	global_store_dwordx4 v[216:217], v[106:109], off offset:512
	global_store_dwordx4 v[216:217], v[94:97], off offset:576
	v_add_co_u32_e32 v214, vcc, 0x120000, v210
	s_nop 1
	v_addc_co_u32_e32 v215, vcc, 0, v211, vcc
	global_load_dwordx4 v[192:195], v[214:215], off
	global_load_dwordx4 v[196:199], v[214:215], off offset:64
	global_load_dwordx4 v[200:203], v[214:215], off offset:512
	global_load_dwordx4 v[204:207], v[214:215], off offset:576
	ds_write_b128 v251, v[122:125]
	ds_read_b128 v[122:125], v252
	ds_write_b128 v251, v[114:117]
	ds_read_b128 v[114:117], v252
	ds_write_b128 v251, v[102:105]
	ds_read_b128 v[102:105], v252
	ds_write_b128 v251, v[90:93]
	ds_read_b128 v[90:93], v252
	v_add_co_u32_e32 v216, vcc, 0x60000, v212
	s_nop 1
	v_addc_co_u32_e32 v217, vcc, 0, v213, vcc
	s_waitcnt vmcnt(16)
	s_waitcnt lgkmcnt(6)
	v_pk_add_f32 v[122:123], v[122:123], v[136:137]
	v_pk_add_f32 v[124:125], v[124:125], v[138:139]
	s_waitcnt lgkmcnt(4)
	v_pk_add_f32 v[114:115], v[114:115], v[140:141]
	v_pk_add_f32 v[116:117], v[116:117], v[142:143]
	s_waitcnt lgkmcnt(2)
	v_pk_add_f32 v[102:103], v[102:103], v[144:145]
	v_pk_add_f32 v[104:105], v[104:105], v[146:147]
	s_waitcnt lgkmcnt(0)
	v_pk_add_f32 v[90:91], v[90:91], v[148:149]
	v_pk_add_f32 v[92:93], v[92:93], v[150:151]
	global_store_dwordx4 v[216:217], v[122:125], off
	global_store_dwordx4 v[216:217], v[114:117], off offset:64
	global_store_dwordx4 v[216:217], v[102:105], off offset:512
	global_store_dwordx4 v[216:217], v[90:93], off offset:576
	v_add_co_u32_e32 v214, vcc, 0x140000, v210
	s_nop 1
	v_addc_co_u32_e32 v215, vcc, 0, v211, vcc
	global_load_dwordx4 v[136:139], v[214:215], off
	global_load_dwordx4 v[140:143], v[214:215], off offset:64
	global_load_dwordx4 v[144:147], v[214:215], off offset:512
	global_load_dwordx4 v[148:151], v[214:215], off offset:576
	ds_write_b128 v251, v[62:65]
	ds_read_b128 v[62:65], v252
	ds_write_b128 v251, v[58:61]
	ds_read_b128 v[58:61], v252
	ds_write_b128 v251, v[54:57]
	ds_read_b128 v[54:57], v252
	ds_write_b128 v251, v[50:53]
	ds_read_b128 v[50:53], v252
	v_add_co_u32_e32 v216, vcc, 0x100000, v212
	s_nop 1
	v_addc_co_u32_e32 v217, vcc, 0, v213, vcc
	s_waitcnt vmcnt(16)
	s_waitcnt lgkmcnt(6)
	v_pk_add_f32 v[62:63], v[62:63], v[160:161]
	v_pk_add_f32 v[64:65], v[64:65], v[162:163]
	s_waitcnt lgkmcnt(4)
;     __device__ __forceinline__ void operator()(f32x4 (&acc)[2][2][4][2], const UnitD& u, int wr, int wc, int fr, int fq) const {
;         const int row0 = u.pm * BM + wr * 64 + fr, col0 = u.pn * BM + wc * 32 + 4 * fq;
; #pragma unroll
;         for (int ai = 0; ai < 2; ++ai)
; #pragma unroll
;             for (int m = 0; m < 4; ++m) { const int row = row0 + ai * HALF + m * 16;
;                 const float* xr = (row < TP ? xp + (size_t)row * 2048 : xs + (size_t)(row - TP) * 2048) + col0;
; #pragma unroll
;                 for (int bj = 0; bj < 2; ++bj)
; #pragma unroll
;                     for (int n = 0; n < 2; ++n) acc[ai][bj][m][n] += *(const f32x4*)(xr + bj * HALF + n * 16);
;                 if (m & 1) asm volatile("" ::: "memory"); }
; #pragma unroll
;         for (int ai = 0; ai < 2; ++ai)
; #pragma unroll
;             for (int m = 0; m < 4; ++m) { const int row = row0 + ai * HALF + m * 16; float* orow = out + (size_t)row * 2048 + col0;
; #pragma unroll
;                 for (int bj = 0; bj < 2; ++bj)
; #pragma unroll
;                     for (int n = 0; n < 2; ++n) *(f32x4*)(orow + bj * HALF + n * 16) = acc[ai][bj][m][n]; }
	v_pk_add_f32 v[58:59], v[58:59], v[164:165]
	v_pk_add_f32 v[60:61], v[60:61], v[166:167]
	s_waitcnt lgkmcnt(2)
	v_pk_add_f32 v[54:55], v[54:55], v[168:169]
	v_pk_add_f32 v[56:57], v[56:57], v[170:171]
	s_waitcnt lgkmcnt(0)
	v_pk_add_f32 v[50:51], v[50:51], v[172:173]
	v_pk_add_f32 v[52:53], v[52:53], v[174:175]
	global_store_dwordx4 v[216:217], v[62:65], off
	global_store_dwordx4 v[216:217], v[58:61], off offset:64
	global_store_dwordx4 v[216:217], v[54:57], off offset:512
	global_store_dwordx4 v[216:217], v[50:53], off offset:576
	v_add_co_u32_e32 v214, vcc, 0x160000, v210
	s_nop 1
	v_addc_co_u32_e32 v215, vcc, 0, v211, vcc
	global_load_dwordx4 v[160:163], v[214:215], off
	global_load_dwordx4 v[164:167], v[214:215], off offset:64
	global_load_dwordx4 v[168:171], v[214:215], off offset:512
	global_load_dwordx4 v[172:175], v[214:215], off offset:576
	ds_write_b128 v251, v[46:49]
	ds_read_b128 v[46:49], v252
	ds_write_b128 v251, v[42:45]
	ds_read_b128 v[42:45], v252
	ds_write_b128 v251, v[38:41]
	ds_read_b128 v[38:41], v252
	ds_write_b128 v251, v[34:37]
	ds_read_b128 v[34:37], v252
	v_add_co_u32_e32 v216, vcc, 0x120000, v212
	s_nop 1
	v_addc_co_u32_e32 v217, vcc, 0, v213, vcc
	s_waitcnt vmcnt(16)
	s_waitcnt lgkmcnt(6)
	v_pk_add_f32 v[46:47], v[46:47], v[192:193]
	v_pk_add_f32 v[48:49], v[48:49], v[194:195]
	s_waitcnt lgkmcnt(4)
	v_pk_add_f32 v[42:43], v[42:43], v[196:197]
	v_pk_add_f32 v[44:45], v[44:45], v[198:199]
	s_waitcnt lgkmcnt(2)
	v_pk_add_f32 v[38:39], v[38:39], v[200:201]
	v_pk_add_f32 v[40:41], v[40:41], v[202:203]
	s_waitcnt lgkmcnt(0)
	v_pk_add_f32 v[34:35], v[34:35], v[204:205]
	v_pk_add_f32 v[36:37], v[36:37], v[206:207]
	global_store_dwordx4 v[216:217], v[46:49], off
	global_store_dwordx4 v[216:217], v[42:45], off offset:64
	global_store_dwordx4 v[216:217], v[38:41], off offset:512
	global_store_dwordx4 v[216:217], v[34:37], off offset:576
	ds_write_b128 v251, v[30:33]
	ds_read_b128 v[30:33], v252
	ds_write_b128 v251, v[26:29]
	ds_read_b128 v[26:29], v252
	ds_write_b128 v251, v[22:25]
	ds_read_b128 v[22:25], v252
	ds_write_b128 v251, v[18:21]
	ds_read_b128 v[18:21], v252
	v_add_co_u32_e32 v216, vcc, 0x140000, v212
	s_nop 1
	v_addc_co_u32_e32 v217, vcc, 0, v213, vcc
	s_waitcnt vmcnt(12)
	s_waitcnt lgkmcnt(6)
	v_pk_add_f32 v[30:31], v[30:31], v[136:137]
	v_pk_add_f32 v[32:33], v[32:33], v[138:139]
	s_waitcnt lgkmcnt(4)
	v_pk_add_f32 v[26:27], v[26:27], v[140:141]
	v_pk_add_f32 v[28:29], v[28:29], v[142:143]
	s_waitcnt lgkmcnt(2)
	v_pk_add_f32 v[22:23], v[22:23], v[144:145]
	v_pk_add_f32 v[24:25], v[24:25], v[146:147]
	s_waitcnt lgkmcnt(0)
	v_pk_add_f32 v[18:19], v[18:19], v[148:149]
	v_pk_add_f32 v[20:21], v[20:21], v[150:151]
	global_store_dwordx4 v[216:217], v[30:33], off
	global_store_dwordx4 v[216:217], v[26:29], off offset:64
	global_store_dwordx4 v[216:217], v[22:25], off offset:512
	global_store_dwordx4 v[216:217], v[18:21], off offset:576
	ds_write_b128 v251, v[14:17]
	ds_read_b128 v[14:17], v252
	ds_write_b128 v251, v[10:13]
	ds_read_b128 v[10:13], v252
	ds_write_b128 v251, v[6:9]
	ds_read_b128 v[6:9], v252
	ds_write_b128 v251, v[2:5]
	ds_read_b128 v[2:5], v252
	v_add_co_u32_e32 v216, vcc, 0x160000, v212
	s_nop 1
	v_addc_co_u32_e32 v217, vcc, 0, v213, vcc
	s_waitcnt vmcnt(8)
	s_waitcnt lgkmcnt(6)
	v_pk_add_f32 v[14:15], v[14:15], v[160:161]
	v_pk_add_f32 v[16:17], v[16:17], v[162:163]
	s_waitcnt lgkmcnt(4)
	v_pk_add_f32 v[10:11], v[10:11], v[164:165]
	v_pk_add_f32 v[12:13], v[12:13], v[166:167]
	s_waitcnt lgkmcnt(2)
	v_pk_add_f32 v[6:7], v[6:7], v[168:169]
	v_pk_add_f32 v[8:9], v[8:9], v[170:171]
	s_waitcnt lgkmcnt(0)
	v_pk_add_f32 v[2:3], v[2:3], v[172:173]
	v_pk_add_f32 v[4:5], v[4:5], v[174:175]
	global_store_dwordx4 v[216:217], v[14:17], off
	global_store_dwordx4 v[216:217], v[10:13], off offset:64
	global_store_dwordx4 v[216:217], v[6:9], off offset:512
	global_store_dwordx4 v[216:217], v[2:5], off offset:576
	s_movk_i32 s17, 0x3f50
	s_mov_b32 s39, s18
	s_mov_b32 s40, s16
	s_mov_b64 s[26:27], s[22:23]
	s_mov_b64 s[24:25], s[20:21]
	s_and_b64 vcc, exec, s[14:15]
	s_cbranch_vccz .LBB0_359
	s_waitcnt vmcnt(0)
	s_cmpk_gt_u32 s4, 0xff
	s_cbranch_scc1 .LBB0_370
	s_barrier

; __global__ void __launch_bounds__(NTH, 2) mega(Params p) {
;     extern __shared__ __attribute__((aligned(16))) unsigned char lds_raw[];
	.amdhsa_kernel _Z4mega6Params
		.amdhsa_group_segment_fixed_size 8192
		.amdhsa_private_segment_fixed_size 0
		.amdhsa_kernarg_size 464
		.amdhsa_user_sgpr_count 2
		.amdhsa_user_sgpr_dispatch_ptr 0
		.amdhsa_user_sgpr_queue_ptr 0
		.amdhsa_user_sgpr_kernarg_segment_ptr 1
		.amdhsa_user_sgpr_dispatch_id 0
		.amdhsa_user_sgpr_kernarg_preload_length 0
		.amdhsa_user_sgpr_kernarg_preload_offset 0
		.amdhsa_user_sgpr_private_segment_size 0
		.amdhsa_uses_dynamic_stack 0
		.amdhsa_enable_private_segment 0
		.amdhsa_system_sgpr_workgroup_id_x 1
		.amdhsa_system_sgpr_workgroup_id_y 0
		.amdhsa_system_sgpr_workgroup_id_z 0
		.amdhsa_system_sgpr_workgroup_info 0
		.amdhsa_system_vgpr_workitem_id 2
		.amdhsa_next_free_vgpr 256
		.amdhsa_next_free_sgpr 100
		.amdhsa_accum_offset 256
		.amdhsa_reserve_vcc 1
		.amdhsa_float_round_mode_32 0
		.amdhsa_float_round_mode_16_64 0
		.amdhsa_float_denorm_mode_32 3
		.amdhsa_float_denorm_mode_16_64 3
		.amdhsa_dx10_clamp 1
		.amdhsa_ieee_mode 1
		.amdhsa_fp16_overflow 0
		.amdhsa_tg_split 0
		.amdhsa_exception_fp_ieee_invalid_op 0
		.amdhsa_exception_fp_denorm_src 0
		.amdhsa_exception_fp_ieee_div_zero 0
		.amdhsa_exception_fp_ieee_overflow 0
		.amdhsa_exception_fp_ieee_underflow 0
		.amdhsa_exception_fp_ieee_inexact 0
		.amdhsa_exception_int_div_zero 0
	.end_amdhsa_kernel

; __global__ void __launch_bounds__(NTH, 2) mega(Params p) {
;     extern __shared__ __attribute__((aligned(16))) unsigned char lds_raw[];
amdhsa.kernels:
  - .agpr_count:     0
    .args:
      - .offset:         0
        .size:           208
        .value_kind:     by_value
      - .offset:         208
        .size:           4
        .value_kind:     hidden_block_count_x
      - .offset:         212
        .size:           4
        .value_kind:     hidden_block_count_y
      - .offset:         216
        .size:           4
        .value_kind:     hidden_block_count_z
      - .offset:         220
        .size:           2
        .value_kind:     hidden_group_size_x
      - .offset:         222
        .size:           2
        .value_kind:     hidden_group_size_y
      - .offset:         224
        .size:           2
        .value_kind:     hidden_group_size_z
      - .offset:         226
        .size:           2
        .value_kind:     hidden_remainder_x
      - .offset:         228
        .size:           2
        .value_kind:     hidden_remainder_y
      - .offset:         230
        .size:           2
        .value_kind:     hidden_remainder_z
      - .offset:         248
        .size:           8
        .value_kind:     hidden_global_offset_x
      - .offset:         256
        .size:           8
        .value_kind:     hidden_global_offset_y
      - .offset:         264
        .size:           8
        .value_kind:     hidden_global_offset_z
      - .offset:         272
        .size:           2
        .value_kind:     hidden_grid_dims
      - .offset:         296
        .size:           8
        .value_kind:     hidden_multigrid_sync_arg
      - .offset:         328
        .size:           4
        .value_kind:     hidden_dynamic_lds_size
    .group_segment_fixed_size: 8192
    .kernarg_segment_align: 8
    .kernarg_segment_size: 464
    .language:       OpenCL C
    .language_version:
      - 2
      - 0
    .max_flat_workgroup_size: 512
    .name:           _Z4mega6Params
    .private_segment_fixed_size: 0
    .sgpr_count:     106
    .sgpr_spill_count: 272
    .symbol:         _Z4mega6Params.kd
    .uniform_work_group_size: 1
    .uses_dynamic_stack: false
    .vgpr_count:     256
    .vgpr_spill_count: 0
    .wavefront_size: 64
